# v43 + attention steady-state steps: K-fragment address adds folded into ds_read_b128 immediate offsets, canonicalizing v_max x,x and 0+e0 sum-init removed (~12 VALU fewer per step)
# speedup vs baseline: 1.0088x; 1.0088x over previous
.LBB0_777:
	ds_read_b128 v[44:47], v42 offset:8192
	v_max_f32_e32 v34, v18, v19
	v_max3_f32 v35, v20, v21, v3
	v_max3_f32 v34, v34, v2, v4
	v_max3_f32 v34, v34, v5, v22
	v_max3_f32 v35, v35, v24, v25
	v_max3_f32 v34, v34, v23, v6
	v_max3_f32 v35, v35, v8, v9
	v_max3_f32 v34, v34, v7, v26
	v_max3_f32 v35, v35, v28, v29
	v_max3_f32 v34, v34, v27, v10
	v_max3_f32 v35, v35, v12, v13
	v_max3_f32 v34, v34, v11, v30
	v_max3_f32 v35, v35, v32, v33
	v_max3_f32 v34, v34, v31, v14
	v_max3_f32 v35, v35, v16, v17
	v_max3_f32 v34, v34, v15, v35
	v_mov_b32_e32 v35, v34
	s_nop 1
	v_permlane32_swap_b32_e32 v34, v35
	v_max_f32_e32 v35, v35, v35
	v_max_f32_e32 v34, v34, v34
	v_max_f32_e32 v212, v34, v35
	v_xor_b32_e32 v82, 0x80000000, v212
	v_sub_f32_e32 v10, v10, v212
	v_mov_b32_e32 v83, v82
	v_mov_b32_e32 v84, v82
	v_mov_b32_e32 v85, v82
	v_mov_b32_e32 v86, v82
	v_mov_b32_e32 v87, v82
	v_mov_b32_e32 v88, v82
	v_mov_b32_e32 v89, v82
	v_mov_b32_e32 v90, v82
	v_mov_b32_e32 v91, v82
	v_mov_b32_e32 v92, v82
	v_mov_b32_e32 v93, v82
	v_mov_b32_e32 v94, v82
	v_mov_b32_e32 v95, v82
	v_mov_b32_e32 v96, v82
	v_mov_b32_e32 v97, v82
	v_sub_f32_e32 v18, v18, v212
	v_sub_f32_e32 v34, v2, v212
	v_sub_f32_e32 v19, v19, v212
	v_sub_f32_e32 v35, v3, v212
	v_sub_f32_e32 v20, v20, v212
	v_sub_f32_e32 v43, v4, v212
	v_sub_f32_e32 v21, v21, v212
	v_sub_f32_e32 v48, v5, v212
	v_sub_f32_e32 v22, v22, v212
	v_sub_f32_e32 v49, v6, v212
	v_sub_f32_e32 v23, v23, v212
	v_sub_f32_e32 v50, v7, v212
	v_sub_f32_e32 v24, v24, v212
	v_sub_f32_e32 v51, v8, v212
	v_sub_f32_e32 v25, v25, v212
	v_sub_f32_e32 v52, v9, v212
	v_sub_f32_e32 v26, v26, v212
	v_sub_f32_e32 v27, v27, v212
	v_sub_f32_e32 v11, v11, v212
	v_sub_f32_e32 v28, v28, v212
	v_sub_f32_e32 v53, v12, v212
	v_sub_f32_e32 v12, v29, v212
	v_sub_f32_e32 v29, v13, v212
	v_sub_f32_e32 v13, v30, v212
	v_sub_f32_e32 v14, v14, v212
	v_sub_f32_e32 v30, v31, v212
	v_sub_f32_e32 v15, v15, v212
	v_sub_f32_e32 v31, v32, v212
	v_sub_f32_e32 v16, v16, v212
	v_sub_f32_e32 v32, v33, v212
	v_sub_f32_e32 v17, v17, v212
	s_waitcnt lgkmcnt(0)
	v_mfma_f32_32x32x16_bf16 v[98:113], v[44:47], v[148:151], v[82:97]
	v_exp_f32_e32 v18, v18
	v_exp_f32_e32 v19, v19
	v_exp_f32_e32 v20, v20
	ds_read_b128 v[2:5], v42 offset:8704
	v_exp_f32_e32 v21, v21
	v_add_f32_e32 v6, v19, v18
	v_add_f32_e32 v6, v20, v6
	v_add_f32_e32 v33, v21, v6
	v_exp_f32_e32 v22, v22
	s_waitcnt lgkmcnt(0)
	v_mfma_f32_32x32x16_bf16 v[66:81], v[2:5], v[148:151], v[82:97]
	v_exp_f32_e32 v23, v23
	v_exp_f32_e32 v24, v24
	ds_read_b128 v[6:9], v42 offset:10240
	v_exp_f32_e32 v25, v25
	v_add_f32_e32 v33, v33, v22
	v_add_f32_e32 v2, v23, v33
	v_add_f32_e32 v2, v24, v2
	v_add_f32_e32 v33, v25, v2
	s_waitcnt lgkmcnt(0)
	v_mfma_f32_32x32x16_bf16 v[98:113], v[6:9], v[152:155], v[98:113]
	v_exp_f32_e32 v26, v26
	v_exp_f32_e32 v27, v27
	v_exp_f32_e32 v28, v28
	ds_read_b128 v[2:5], v42 offset:10752
	v_exp_f32_e32 v12, v12
	v_add_f32_e32 v6, v26, v33
	v_add_f32_e32 v6, v27, v6
	v_mov_b32_e32 v147, v146
	v_add_f32_e32 v6, v28, v6
	v_cvt_pk_bf16_f32 v144, v18, v19
	v_cvt_pk_bf16_f32 v145, v20, v21
	v_mov_b64_e32 v[166:167], v[146:147]
	v_add_f32_e32 v33, v12, v6
	v_mov_b64_e32 v[164:165], v[144:145]
	s_waitcnt lgkmcnt(0)
	v_mfma_f32_32x32x16_bf16 v[66:81], v[2:5], v[152:155], v[66:81]
	v_exp_f32_e32 v13, v13
	v_exp_f32_e32 v18, v30
	v_exp_f32_e32 v19, v31
	ds_read_b128 v[6:9], v42 offset:12288
	v_exp_f32_e32 v20, v32
	v_add_f32_e32 v2, v13, v33
	v_add_f32_e32 v2, v18, v2
	v_add_f32_e32 v2, v19, v2
	v_add_f32_e32 v21, v20, v2
	v_cvt_pk_bf16_f32 v166, v22, v23
	v_cvt_pk_bf16_f32 v167, v24, v25
	s_waitcnt lgkmcnt(0)
	v_mfma_f32_32x32x16_bf16 v[98:113], v[6:9], v[156:159], v[98:113]
	v_exp_f32_e32 v22, v34
	ds_read_b128 v[2:5], v42 offset:12800
	v_exp_f32_e32 v23, v35
	v_cvt_pk_bf16_f32 v168, v26, v27
	v_add_f32_e32 v6, v22, v21
	v_cvt_pk_bf16_f32 v169, v28, v12
	v_add_f32_e32 v6, v23, v6
	v_exp_f32_e32 v21, v43
	v_exp_f32_e32 v24, v48
	v_cvt_pk_bf16_f32 v170, v13, v18
	v_cvt_pk_bf16_f32 v171, v19, v20
	v_add_f32_e32 v6, v21, v6
	v_add_f32_e32 v12, v24, v6
	s_waitcnt lgkmcnt(0)
	v_mfma_f32_32x32x16_bf16 v[66:81], v[2:5], v[156:159], v[66:81]
	v_exp_f32_e32 v18, v49
	ds_read_b128 v[6:9], v42 offset:14336
	v_exp_f32_e32 v19, v50
	v_add_f32_e32 v2, v18, v12
	v_add_f32_e32 v2, v19, v2
	v_exp_f32_e32 v20, v51
	v_exp_f32_e32 v25, v52
	v_add_f32_e32 v2, v20, v2
	v_add_f32_e32 v4, v25, v2
	s_waitcnt lgkmcnt(0)
	v_mfma_f32_32x32x16_bf16 v[98:113], v[6:9], v[160:163], v[98:113]
	v_exp_f32_e32 v2, v10
	v_exp_f32_e32 v3, v11
	ds_read_b128 v[10:13], v42 offset:14848
	v_cvt_pk_bf16_f32 v172, v22, v23
	v_add_f32_e32 v4, v2, v4
	v_add_f32_e32 v26, v3, v4
	v_cvt_pk_bf16_f32 v173, v21, v24
	v_exp_f32_e32 v4, v53
	v_exp_f32_e32 v5, v29
	v_cvt_pk_bf16_f32 v174, v18, v19
	v_cvt_pk_bf16_f32 v175, v20, v25
	v_add_f32_e32 v6, v4, v26
	v_add_f32_e32 v8, v5, v6
	s_waitcnt lgkmcnt(0)
	v_mfma_f32_32x32x16_bf16 v[66:81], v[10:13], v[160:163], v[66:81]
	v_exp_f32_e32 v6, v14
	v_exp_f32_e32 v7, v15
	v_add_f32_e32 v8, v6, v8
	v_add_f32_e32 v10, v7, v8
	v_exp_f32_e32 v8, v16
	v_exp_f32_e32 v9, v17
	v_add_f32_e32 v10, v8, v10
	v_add_f32_e32 v10, v9, v10
	s_cmp_lt_i32 s71, 6
	s_cselect_b64 s[76:77], -1, 0
	s_cmp_gt_i32 s71, 5
	s_cbranch_scc1 .LBB0_779
	v_or_b32_e32 v12, 0x60, v1
	v_or_b32_e32 v11, 64, v1
	v_cmp_le_i32_e32 vcc, v12, v185
	s_nop 1
	v_cndmask_b32_e32 v66, v206, v66, vcc
	v_cmp_lt_i32_e32 vcc, v11, v185
	s_nop 1
	v_cndmask_b32_e32 v99, v206, v99, vcc
	v_cmp_le_i32_e32 vcc, v11, v185
	v_or_b32_e32 v11, 0x61, v1
	s_nop 0
	v_cndmask_b32_e32 v98, v206, v98, vcc
	v_cmp_le_i32_e32 vcc, v11, v185
	v_or_b32_e32 v11, 0x42, v1
	s_nop 0
	v_cndmask_b32_e32 v67, v206, v67, vcc
	v_cmp_le_i32_e32 vcc, v11, v185
	v_or_b32_e32 v11, 0x62, v1
	s_nop 0
	v_cndmask_b32_e32 v100, v206, v100, vcc
	v_cmp_le_i32_e32 vcc, v11, v185
	v_or_b32_e32 v11, 0x43, v1
	s_nop 0
	v_cndmask_b32_e32 v68, v206, v68, vcc
	v_cmp_le_i32_e32 vcc, v11, v185
	v_or_b32_e32 v11, 0x63, v1
	s_nop 0
	v_cndmask_b32_e32 v101, v206, v101, vcc
	v_cmp_le_i32_e32 vcc, v11, v185
	v_or_b32_e32 v11, 0x48, v1
	s_nop 0
	v_cndmask_b32_e32 v69, v206, v69, vcc
	v_cmp_le_i32_e32 vcc, v11, v185
	v_or_b32_e32 v11, 0x68, v1
	s_nop 0
	v_cndmask_b32_e32 v102, v206, v102, vcc
	v_cmp_le_i32_e32 vcc, v11, v185
	v_or_b32_e32 v11, 0x49, v1
	s_nop 0
	v_cndmask_b32_e32 v70, v206, v70, vcc
	v_cmp_le_i32_e32 vcc, v11, v185
	v_or_b32_e32 v11, 0x69, v1
	s_nop 0
	v_cndmask_b32_e32 v103, v206, v103, vcc
	v_cmp_le_i32_e32 vcc, v11, v185
	v_or_b32_e32 v11, 0x4a, v1
	s_nop 0
	v_cndmask_b32_e32 v71, v206, v71, vcc
	v_cmp_le_i32_e32 vcc, v11, v185
	v_or_b32_e32 v11, 0x6a, v1
	s_nop 0
	v_cndmask_b32_e32 v104, v206, v104, vcc
	v_cmp_le_i32_e32 vcc, v11, v185
	v_or_b32_e32 v11, 0x4b, v1
	s_nop 0
	v_cndmask_b32_e32 v72, v206, v72, vcc
	v_cmp_le_i32_e32 vcc, v11, v185
	v_or_b32_e32 v11, 0x6b, v1
	s_nop 0
	v_cndmask_b32_e32 v105, v206, v105, vcc
	v_cmp_le_i32_e32 vcc, v11, v185
	v_or_b32_e32 v11, 0x50, v1
	s_nop 0
	v_cndmask_b32_e32 v73, v206, v73, vcc
	v_cmp_le_i32_e32 vcc, v11, v185
	v_or_b32_e32 v11, 0x70, v1
	s_nop 0
	v_cndmask_b32_e32 v106, v206, v106, vcc
	v_cmp_le_i32_e32 vcc, v11, v185
	v_or_b32_e32 v11, 0x51, v1
	s_nop 0
	v_cndmask_b32_e32 v74, v206, v74, vcc
	v_cmp_le_i32_e32 vcc, v11, v185
	v_or_b32_e32 v11, 0x71, v1
	s_nop 0
	v_cndmask_b32_e32 v107, v206, v107, vcc
	v_cmp_le_i32_e32 vcc, v11, v185
	v_or_b32_e32 v11, 0x52, v1
	s_nop 0
	v_cndmask_b32_e32 v75, v206, v75, vcc
	v_cmp_le_i32_e32 vcc, v11, v185
	v_or_b32_e32 v11, 0x72, v1
	s_nop 0
	v_cndmask_b32_e32 v108, v206, v108, vcc
	v_cmp_le_i32_e32 vcc, v11, v185
	v_or_b32_e32 v11, 0x53, v1
	s_nop 0
	v_cndmask_b32_e32 v76, v206, v76, vcc
	v_cmp_le_i32_e32 vcc, v11, v185
	v_or_b32_e32 v11, 0x73, v1
	s_nop 0
	v_cndmask_b32_e32 v109, v206, v109, vcc
	v_cmp_le_i32_e32 vcc, v11, v185
	v_or_b32_e32 v11, 0x58, v1
	s_nop 0
	v_cndmask_b32_e32 v77, v206, v77, vcc
	v_cmp_le_i32_e32 vcc, v11, v185
	v_or_b32_e32 v11, 0x78, v1
	s_nop 0
	v_cndmask_b32_e32 v110, v206, v110, vcc
	v_cmp_le_i32_e32 vcc, v11, v185
	v_or_b32_e32 v11, 0x59, v1
	s_nop 0
	v_cndmask_b32_e32 v78, v206, v78, vcc
	v_cmp_le_i32_e32 vcc, v11, v185
	v_or_b32_e32 v11, 0x79, v1
	s_nop 0
	v_cndmask_b32_e32 v111, v206, v111, vcc
	v_cmp_le_i32_e32 vcc, v11, v185
	v_or_b32_e32 v11, 0x5a, v1
	s_nop 0
	v_cndmask_b32_e32 v79, v206, v79, vcc
	v_cmp_le_i32_e32 vcc, v11, v185
	v_or_b32_e32 v11, 0x7a, v1
	s_nop 0
	v_cndmask_b32_e32 v112, v206, v112, vcc
	v_cmp_le_i32_e32 vcc, v11, v185
	v_or_b32_e32 v11, 0x5b, v1
	v_or_b32_e32 v1, 0x7b, v1
	v_cndmask_b32_e32 v80, v206, v80, vcc
	v_cmp_le_i32_e32 vcc, v11, v185
	s_nop 1
	v_cndmask_b32_e32 v113, v206, v113, vcc
	v_cmp_le_i32_e32 vcc, v1, v185
	s_nop 1
	v_cndmask_b32_e32 v81, v206, v81, vcc

.LBB0_789:
	s_mul_hi_u32 s4, s61, 0xaaaaaaab
	s_lshr_b32 s50, s4, 1
	s_mul_i32 s4, s50, 0xffffa000
	s_add_i32 s4, s14, s4
	s_and_b32 s51, s14, 0x6000
	v_add_u32_e32 v217, s4, v214
	v_add_u32_e32 v216, s51, v147
	v_add_u32_e32 v217, 0xffffc000, v217
	ds_read_b64_tr_b16 v[118:119], v216 offset:24576
	ds_read_b64_tr_b16 v[120:121], v216 offset:25088
	ds_read_b64_tr_b16 v[122:123], v216 offset:28672
	ds_read_b64_tr_b16 v[124:125], v216 offset:29184
	ds_read_b128 v[114:117], v217
	s_waitcnt lgkmcnt(3)
	v_mfma_f32_32x32x16_bf16 v[18:33], v[164:167], v[118:121], v[18:33]
	ds_read_b64_tr_b16 v[126:127], v216 offset:57344
	ds_read_b64_tr_b16 v[128:129], v216 offset:57856
	s_waitcnt lgkmcnt(3)
	v_mfma_f32_32x32x16_bf16 v[50:65], v[164:167], v[122:125], v[50:65]
	ds_read_b64_tr_b16 v[130:131], v216 offset:61440
	ds_read_b64_tr_b16 v[132:133], v216 offset:61952
	s_waitcnt lgkmcnt(2)
	v_mfma_f32_32x32x16_bf16 v[34:49], v[164:167], v[126:129], v[34:49]
	ds_read_b64_tr_b16 v[118:119], v216 offset:25600
	ds_read_b64_tr_b16 v[120:121], v216 offset:26112
	s_waitcnt lgkmcnt(2)
	v_mfma_f32_32x32x16_bf16 v[2:17], v[164:167], v[130:133], v[2:17]
	ds_read_b64_tr_b16 v[180:181], v216 offset:29696
	ds_read_b64_tr_b16 v[182:183], v216 offset:30208
	v_max_f32_e32 v122, v98, v99
	v_max3_f32 v123, v100, v101, v67
	v_max3_f32 v122, v122, v66, v68
	v_max3_f32 v122, v122, v69, v102
	v_max3_f32 v123, v123, v104, v105
	v_max3_f32 v122, v122, v103, v70
	v_max3_f32 v123, v123, v72, v73
	v_max3_f32 v122, v122, v71, v106
	v_max3_f32 v123, v123, v108, v109
	v_max3_f32 v122, v122, v107, v74
	v_max3_f32 v123, v123, v76, v77
	v_max3_f32 v122, v122, v75, v110
	v_max3_f32 v123, v123, v112, v113
	v_max3_f32 v122, v122, v111, v78
	v_max3_f32 v123, v123, v80, v81
	v_max3_f32 v122, v122, v79, v123
	v_mov_b32_e32 v123, v122
	s_nop 1
	v_permlane32_swap_b32_e32 v122, v123
	v_max_f32_e32 v122, v122, v123
	v_cmp_lt_f32_e32 vcc, s15, v122
	s_cmp_lg_u64 vcc, 0
	s_cselect_b64 s[4:5], -1, 0
	s_cbranch_vccz .LBB0_793
	v_max_f32_e32 v82, v122, v122
	v_max_f32_e32 v122, 0, v82
	v_exp_f32_e64 v123, -v122
	v_add_f32_e32 v212, v212, v122
	v_xor_b32_e32 v82, 0x80000000, v212
	v_mov_b32_e32 v83, v82
	v_mov_b32_e32 v84, v82
	v_mov_b32_e32 v85, v82
	v_mov_b32_e32 v86, v82
	v_mov_b32_e32 v87, v82
	v_mov_b32_e32 v88, v82
	v_mov_b32_e32 v89, v82
	v_mov_b32_e32 v90, v82
	v_mov_b32_e32 v91, v82
	v_mov_b32_e32 v92, v82
	v_mov_b32_e32 v93, v82
	v_mov_b32_e32 v94, v82
	v_mov_b32_e32 v95, v82
	v_mov_b32_e32 v96, v82
	v_mov_b32_e32 v97, v82
	s_and_saveexec_b64 vcc, s[8:9]
	ds_write_b32 v1, v123
	s_or_b64 exec, exec, vcc
	v_sub_f32_e32 v113, v113, v122
	v_sub_f32_e32 v112, v112, v122
	v_sub_f32_e32 v111, v111, v122
	v_sub_f32_e32 v110, v110, v122
	v_sub_f32_e32 v109, v109, v122
	v_sub_f32_e32 v108, v108, v122
	v_sub_f32_e32 v107, v107, v122
	v_sub_f32_e32 v106, v106, v122
	v_sub_f32_e32 v105, v105, v122
	v_sub_f32_e32 v104, v104, v122
	v_sub_f32_e32 v103, v103, v122
	v_sub_f32_e32 v102, v102, v122
	v_sub_f32_e32 v101, v101, v122
	v_sub_f32_e32 v100, v100, v122
	v_sub_f32_e32 v99, v99, v122
	v_sub_f32_e32 v98, v98, v122
	v_sub_f32_e32 v81, v81, v122
	v_sub_f32_e32 v80, v80, v122
	v_sub_f32_e32 v79, v79, v122
	v_sub_f32_e32 v78, v78, v122
	v_sub_f32_e32 v77, v77, v122
	v_sub_f32_e32 v76, v76, v122
	v_sub_f32_e32 v75, v75, v122
	v_sub_f32_e32 v74, v74, v122
	v_sub_f32_e32 v73, v73, v122
	v_sub_f32_e32 v72, v72, v122
	v_sub_f32_e32 v71, v71, v122
	v_sub_f32_e32 v70, v70, v122
	v_sub_f32_e32 v69, v69, v122
	v_sub_f32_e32 v68, v68, v122
	v_sub_f32_e32 v67, v67, v122
	v_sub_f32_e32 v66, v66, v122
	v_mul_f32_e32 v213, v213, v123
.LBB0_793:
	v_exp_f32_e32 v164, v98
	v_mfma_f32_32x32x16_bf16 v[130:145], v[114:117], v[148:151], v[82:97]
	v_exp_f32_e32 v165, v99
	v_exp_f32_e32 v230, v100
	ds_read_b64_tr_b16 v[218:219], v216 offset:58368
	ds_read_b64_tr_b16 v[220:221], v216 offset:58880
	v_exp_f32_e32 v231, v101
	ds_read_b128 v[222:225], v217 offset:512
	s_waitcnt lgkmcnt(5)
	v_mfma_f32_32x32x16_bf16 v[18:33], v[168:171], v[118:121], v[18:33]
	v_add_f32_e32 v98, v165, v164
	v_add_f32_e32 v98, v230, v98
	v_add_f32_e32 v232, v231, v98
	ds_read_b64_tr_b16 v[98:99], v216 offset:62464
	ds_read_b64_tr_b16 v[100:101], v216 offset:62976
	ds_read_b128 v[226:229], v217 offset:2048
	v_exp_f32_e32 v233, v102
	s_waitcnt lgkmcnt(3)
	v_mfma_f32_32x32x16_bf16 v[114:129], v[222:225], v[148:151], v[82:97]
	v_exp_f32_e32 v222, v103
	v_exp_f32_e32 v223, v104
	v_exp_f32_e32 v224, v105
	v_add_f32_e32 v102, v233, v232
	v_add_f32_e32 v102, v222, v102
	v_add_f32_e32 v102, v223, v102
	v_add_f32_e32 v225, v224, v102
	v_mfma_f32_32x32x16_bf16 v[50:65], v[168:171], v[180:183], v[50:65]
	v_exp_f32_e32 v232, v106
	s_waitcnt lgkmcnt(0)
	v_mfma_f32_32x32x16_bf16 v[130:145], v[226:229], v[152:155], v[130:145]
	v_exp_f32_e32 v234, v107
	v_exp_f32_e32 v226, v108
	ds_read_b64_tr_b16 v[102:103], v216 offset:26624
	ds_read_b64_tr_b16 v[104:105], v216 offset:27136
	v_exp_f32_e32 v227, v109
	ds_read_b128 v[180:183], v217 offset:2560
	v_add_f32_e32 v106, v232, v225
	v_mfma_f32_32x32x16_bf16 v[34:49], v[168:171], v[218:221], v[34:49]
	v_add_f32_e32 v106, v234, v106
	v_add_f32_e32 v106, v226, v106
	v_add_f32_e32 v225, v227, v106
	v_cvt_pk_bf16_f32 v164, v164, v165
	v_cvt_pk_bf16_f32 v165, v230, v231
	v_exp_f32_e32 v228, v110
	s_waitcnt lgkmcnt(0)
	v_mfma_f32_32x32x16_bf16 v[114:129], v[180:183], v[152:155], v[114:129]
	v_exp_f32_e32 v229, v111
	v_exp_f32_e32 v180, v112
	ds_read_b64_tr_b16 v[106:107], v216 offset:30720
	ds_read_b64_tr_b16 v[108:109], v216 offset:31232
	v_exp_f32_e32 v181, v113
	ds_read_b128 v[218:221], v217 offset:4096
	v_add_f32_e32 v110, v228, v225
	v_mfma_f32_32x32x16_bf16 v[2:17], v[168:171], v[98:101], v[2:17]
	v_add_f32_e32 v110, v229, v110
	v_add_f32_e32 v110, v180, v110
	v_add_f32_e32 v182, v181, v110
	v_cvt_pk_bf16_f32 v166, v233, v222
	v_cvt_pk_bf16_f32 v167, v223, v224
	s_waitcnt lgkmcnt(0)
	v_mfma_f32_32x32x16_bf16 v[130:145], v[218:221], v[156:159], v[130:145]
	v_exp_f32_e32 v183, v66
	ds_read_b64_tr_b16 v[98:99], v216 offset:59392
	ds_read_b64_tr_b16 v[100:101], v216 offset:59904
	v_exp_f32_e32 v222, v67
	ds_read_b128 v[110:113], v217 offset:4608
	v_add_f32_e32 v66, v183, v182
	v_cvt_pk_bf16_f32 v168, v232, v234
	v_mfma_f32_32x32x16_bf16 v[18:33], v[172:175], v[102:105], v[18:33]
	v_add_f32_e32 v66, v222, v66
	v_cvt_pk_bf16_f32 v169, v226, v227
	v_mfma_f32_32x32x16_bf16 v[50:65], v[172:175], v[106:109], v[50:65]
	v_exp_f32_e32 v182, v68
	ds_read_b64_tr_b16 v[102:103], v216 offset:63488
	ds_read_b64_tr_b16 v[104:105], v216 offset:64000
	v_exp_f32_e32 v218, v69
	v_cvt_pk_bf16_f32 v170, v228, v229
	v_add_f32_e32 v66, v182, v66
	v_cvt_pk_bf16_f32 v171, v180, v181
	v_add_f32_e32 v219, v218, v66
	s_waitcnt lgkmcnt(2)
	v_mfma_f32_32x32x16_bf16 v[114:129], v[110:113], v[156:159], v[114:129]
	v_exp_f32_e32 v110, v70
	ds_read_b64_tr_b16 v[66:67], v216 offset:27648
	ds_read_b64_tr_b16 v[68:69], v216 offset:28160
	v_exp_f32_e32 v111, v71
	ds_read_b128 v[106:109], v217 offset:6144
	v_add_f32_e32 v70, v110, v219
	v_add_f32_e32 v70, v111, v70
	v_mfma_f32_32x32x16_bf16 v[34:49], v[172:175], v[98:101], v[34:49]
	s_waitcnt lgkmcnt(3)
	v_mfma_f32_32x32x16_bf16 v[2:17], v[172:175], v[102:105], v[2:17]
	v_exp_f32_e32 v112, v72
	ds_read_b64_tr_b16 v[98:99], v216 offset:31744
	ds_read_b64_tr_b16 v[100:101], v216 offset:32256
	v_exp_f32_e32 v113, v73
	v_add_f32_e32 v70, v112, v70
	v_add_f32_e32 v172, v113, v70
	s_waitcnt lgkmcnt(2)
	v_mfma_f32_32x32x16_bf16 v[130:145], v[106:109], v[160:163], v[130:145]
	v_exp_f32_e32 v74, v74
	ds_read_b64_tr_b16 v[70:71], v216 offset:60416
	ds_read_b64_tr_b16 v[72:73], v216 offset:60928
	v_exp_f32_e32 v75, v75
	ds_read_b128 v[102:105], v217 offset:6656
	v_add_f32_e32 v106, v74, v172
	v_cvt_pk_bf16_f32 v172, v183, v222
	v_mfma_f32_32x32x16_bf16 v[18:33], v[176:179], v[66:69], v[18:33]
	v_add_f32_e32 v106, v75, v106
	v_cvt_pk_bf16_f32 v173, v182, v218
	s_waitcnt lgkmcnt(3)
	v_mfma_f32_32x32x16_bf16 v[50:65], v[176:179], v[98:101], v[50:65]
	v_exp_f32_e32 v76, v76
	v_exp_f32_e32 v77, v77
	ds_read_b64_tr_b16 v[66:67], v216 offset:64512
	ds_read_b64_tr_b16 v[68:69], v216 offset:65024
	v_cvt_pk_bf16_f32 v174, v110, v111
	v_add_f32_e32 v106, v76, v106
	v_add_f32_e32 v106, v77, v106
	v_cvt_pk_bf16_f32 v175, v112, v113
	s_waitcnt lgkmcnt(2)
	v_mfma_f32_32x32x16_bf16 v[114:129], v[102:105], v[160:163], v[114:129]
	v_exp_f32_e32 v78, v78
	v_exp_f32_e32 v79, v79
	v_add_f32_e32 v98, v78, v106
	v_add_f32_e32 v98, v79, v98
	v_mfma_f32_32x32x16_bf16 v[34:49], v[176:179], v[70:73], v[34:49]
	s_waitcnt lgkmcnt(0)
	v_mfma_f32_32x32x16_bf16 v[2:17], v[176:179], v[66:69], v[2:17]
	v_exp_f32_e32 v80, v80
	v_exp_f32_e32 v81, v81
	v_add_f32_e32 v66, v80, v98
	v_add_f32_e32 v66, v81, v66
	s_andn2_b64 vcc, exec, s[4:5]
	s_cbranch_vccnz .LBB0_795
	s_waitcnt lgkmcnt(0)
	ds_read_b128 v[68:71], v215 offset:96
	ds_read_b128 v[98:101], v215 offset:64
	ds_read_b128 v[102:105], v215 offset:32
	ds_read_b128 v[106:109], v215
	s_waitcnt lgkmcnt(0)
	s_waitcnt lgkmcnt(3)
	v_pk_mul_f32 v[30:31], v[30:31], v[68:69]
	s_waitcnt lgkmcnt(2)
	v_pk_mul_f32 v[26:27], v[26:27], v[98:99]
	s_waitcnt lgkmcnt(1)
	v_pk_mul_f32 v[22:23], v[22:23], v[102:103]
	v_pk_mul_f32 v[32:33], v[32:33], v[70:71]
	v_pk_mul_f32 v[28:29], v[28:29], v[100:101]
	v_pk_mul_f32 v[24:25], v[24:25], v[104:105]
	s_waitcnt lgkmcnt(0)
	v_pk_mul_f32 v[20:21], v[20:21], v[108:109]
	v_pk_mul_f32 v[18:19], v[18:19], v[106:107]
	v_pk_mul_f32 v[62:63], v[62:63], v[68:69]
	v_pk_mul_f32 v[58:59], v[58:59], v[98:99]
	v_pk_mul_f32 v[54:55], v[54:55], v[102:103]
	v_pk_mul_f32 v[64:65], v[64:65], v[70:71]
	v_pk_mul_f32 v[60:61], v[60:61], v[100:101]
	v_pk_mul_f32 v[56:57], v[56:57], v[104:105]
	v_pk_mul_f32 v[52:53], v[52:53], v[108:109]
	v_pk_mul_f32 v[50:51], v[50:51], v[106:107]
	v_pk_mul_f32 v[46:47], v[46:47], v[68:69]
	v_pk_mul_f32 v[42:43], v[42:43], v[98:99]
	v_pk_mul_f32 v[38:39], v[38:39], v[102:103]
	v_pk_mul_f32 v[48:49], v[48:49], v[70:71]
	v_pk_mul_f32 v[44:45], v[44:45], v[100:101]
	v_pk_mul_f32 v[40:41], v[40:41], v[104:105]
	v_pk_mul_f32 v[36:37], v[36:37], v[108:109]
	v_pk_mul_f32 v[34:35], v[34:35], v[106:107]
	v_pk_mul_f32 v[14:15], v[14:15], v[68:69]
	v_pk_mul_f32 v[10:11], v[10:11], v[98:99]
	v_pk_mul_f32 v[6:7], v[6:7], v[102:103]
	v_pk_mul_f32 v[16:17], v[16:17], v[70:71]
	v_pk_mul_f32 v[12:13], v[12:13], v[100:101]
	v_pk_mul_f32 v[8:9], v[8:9], v[104:105]
	v_pk_mul_f32 v[4:5], v[4:5], v[108:109]
	v_pk_mul_f32 v[2:3], v[2:3], v[106:107]

.LBB0_802:
	s_mul_hi_u32 s4, s30, 0xaaaaaaab
	s_lshr_b32 s4, s4, 1
	s_mulk_i32 s4, 0xa000
	s_add_i32 s5, s14, 0xffffa000
	s_add_i32 s4, s14, s4
	s_and_b32 s5, s5, 0x6000
	v_add_u32_e32 v194, s4, v214
	v_add_f32_e32 v192, v213, v66
	v_add_u32_e32 v193, s5, v147
	v_add_u32_e32 v194, 0xffffe000, v194
	ds_read_b64_tr_b16 v[70:71], v193 offset:24576
	ds_read_b64_tr_b16 v[72:73], v193 offset:25088
	ds_read_b64_tr_b16 v[98:99], v193 offset:28672
	ds_read_b64_tr_b16 v[100:101], v193 offset:29184
	ds_read_b128 v[66:69], v194
	s_waitcnt lgkmcnt(3)
	v_mfma_f32_32x32x16_bf16 v[18:33], v[164:167], v[70:73], v[18:33]
	ds_read_b64_tr_b16 v[102:103], v193 offset:57344
	ds_read_b64_tr_b16 v[104:105], v193 offset:57856
	s_waitcnt lgkmcnt(3)
	v_mfma_f32_32x32x16_bf16 v[50:65], v[164:167], v[98:101], v[50:65]
	ds_read_b64_tr_b16 v[106:107], v193 offset:61440
	ds_read_b64_tr_b16 v[108:109], v193 offset:61952
	s_waitcnt lgkmcnt(2)
	v_mfma_f32_32x32x16_bf16 v[34:49], v[164:167], v[102:105], v[34:49]
	ds_read_b64_tr_b16 v[70:71], v193 offset:25600
	ds_read_b64_tr_b16 v[72:73], v193 offset:26112
	s_waitcnt lgkmcnt(2)
	v_mfma_f32_32x32x16_bf16 v[2:17], v[164:167], v[106:109], v[2:17]
	ds_read_b64_tr_b16 v[180:181], v193 offset:29696
	ds_read_b64_tr_b16 v[182:183], v193 offset:30208
	v_max_f32_e32 v98, v130, v131
	v_max3_f32 v99, v132, v133, v115
	v_max3_f32 v98, v98, v114, v116
	v_max3_f32 v98, v98, v117, v134
	v_max3_f32 v99, v99, v136, v137
	v_max3_f32 v98, v98, v135, v118
	v_max3_f32 v99, v99, v120, v121
	v_max3_f32 v98, v98, v119, v138
	v_max3_f32 v99, v99, v140, v141
	v_max3_f32 v98, v98, v139, v122
	v_max3_f32 v99, v99, v124, v125
	v_max3_f32 v98, v98, v123, v142
	v_max3_f32 v99, v99, v144, v145
	v_max3_f32 v98, v98, v143, v126
	v_max3_f32 v99, v99, v128, v129
	v_max3_f32 v98, v98, v127, v99
	v_mov_b32_e32 v99, v98
	s_nop 1
	v_permlane32_swap_b32_e32 v98, v99
	v_max_f32_e32 v98, v98, v99
	v_cmp_lt_f32_e32 vcc, s15, v98
	s_cmp_lg_u64 vcc, 0
	s_cselect_b64 s[4:5], -1, 0
	s_cbranch_vccz .LBB0_806
	v_max_f32_e32 v82, v98, v98
	v_max_f32_e32 v98, 0, v82
	v_exp_f32_e64 v99, -v98
	v_add_f32_e32 v212, v212, v98
	v_xor_b32_e32 v82, 0x80000000, v212
	v_mov_b32_e32 v83, v82
	v_mov_b32_e32 v84, v82
	v_mov_b32_e32 v85, v82
	v_mov_b32_e32 v86, v82
	v_mov_b32_e32 v87, v82
	v_mov_b32_e32 v88, v82
	v_mov_b32_e32 v89, v82
	v_mov_b32_e32 v90, v82
	v_mov_b32_e32 v91, v82
	v_mov_b32_e32 v92, v82
	v_mov_b32_e32 v93, v82
	v_mov_b32_e32 v94, v82
	v_mov_b32_e32 v95, v82
	v_mov_b32_e32 v96, v82
	v_mov_b32_e32 v97, v82
	s_and_saveexec_b64 s[22:23], s[8:9]
	ds_write_b32 v1, v99
	s_or_b64 exec, exec, s[22:23]
	v_sub_f32_e32 v145, v145, v98
	v_sub_f32_e32 v144, v144, v98
	v_sub_f32_e32 v143, v143, v98
	v_sub_f32_e32 v142, v142, v98
	v_sub_f32_e32 v141, v141, v98
	v_sub_f32_e32 v140, v140, v98
	v_sub_f32_e32 v139, v139, v98
	v_sub_f32_e32 v138, v138, v98
	v_sub_f32_e32 v137, v137, v98
	v_sub_f32_e32 v136, v136, v98
	v_sub_f32_e32 v135, v135, v98
	v_sub_f32_e32 v134, v134, v98
	v_sub_f32_e32 v133, v133, v98
	v_sub_f32_e32 v132, v132, v98
	v_sub_f32_e32 v131, v131, v98
	v_sub_f32_e32 v130, v130, v98
	v_sub_f32_e32 v129, v129, v98
	v_sub_f32_e32 v128, v128, v98
	v_sub_f32_e32 v127, v127, v98
	v_sub_f32_e32 v126, v126, v98
	v_sub_f32_e32 v125, v125, v98
	v_sub_f32_e32 v124, v124, v98
	v_sub_f32_e32 v123, v123, v98
	v_sub_f32_e32 v122, v122, v98
	v_sub_f32_e32 v121, v121, v98
	v_sub_f32_e32 v120, v120, v98
	v_sub_f32_e32 v119, v119, v98
	v_sub_f32_e32 v118, v118, v98
	v_sub_f32_e32 v117, v117, v98
	v_sub_f32_e32 v116, v116, v98
	v_sub_f32_e32 v115, v115, v98
	v_sub_f32_e32 v114, v114, v98
	v_mul_f32_e32 v192, v192, v99
.LBB0_806:
	v_cvt_pk_bf16_f32 v176, v74, v75
	v_cvt_pk_bf16_f32 v177, v76, v77
	v_cvt_pk_bf16_f32 v178, v78, v79
	v_cvt_pk_bf16_f32 v179, v80, v81
	v_exp_f32_e32 v164, v130
	v_mfma_f32_32x32x16_bf16 v[98:113], v[66:69], v[148:151], v[82:97]
	v_exp_f32_e32 v165, v131
	v_exp_f32_e32 v195, v132
	ds_read_b64_tr_b16 v[216:217], v193 offset:58368
	ds_read_b64_tr_b16 v[218:219], v193 offset:58880
	v_exp_f32_e32 v213, v133
	ds_read_b128 v[220:223], v194 offset:512
	s_waitcnt lgkmcnt(5)
	v_mfma_f32_32x32x16_bf16 v[18:33], v[168:171], v[70:73], v[18:33]
	v_add_f32_e32 v66, v165, v164
	v_add_f32_e32 v66, v195, v66
	v_add_f32_e32 v228, v213, v66
	ds_read_b64_tr_b16 v[130:131], v193 offset:62464
	ds_read_b64_tr_b16 v[132:133], v193 offset:62976
	ds_read_b128 v[224:227], v194 offset:2048
	v_exp_f32_e32 v229, v134
	s_waitcnt lgkmcnt(3)
	v_mfma_f32_32x32x16_bf16 v[66:81], v[220:223], v[148:151], v[82:97]
	v_exp_f32_e32 v220, v135
	v_exp_f32_e32 v221, v136
	v_exp_f32_e32 v222, v137
	v_add_f32_e32 v134, v229, v228
	v_add_f32_e32 v134, v220, v134
	v_add_f32_e32 v134, v221, v134
	v_add_f32_e32 v223, v222, v134
	v_mfma_f32_32x32x16_bf16 v[50:65], v[168:171], v[180:183], v[50:65]
	v_exp_f32_e32 v228, v138
	s_waitcnt lgkmcnt(0)
	v_mfma_f32_32x32x16_bf16 v[98:113], v[224:227], v[152:155], v[98:113]
	v_exp_f32_e32 v230, v139
	v_exp_f32_e32 v224, v140
	ds_read_b64_tr_b16 v[134:135], v193 offset:26624
	ds_read_b64_tr_b16 v[136:137], v193 offset:27136
	v_exp_f32_e32 v225, v141
	ds_read_b128 v[180:183], v194 offset:2560
	v_add_f32_e32 v138, v228, v223
	v_mfma_f32_32x32x16_bf16 v[34:49], v[168:171], v[216:219], v[34:49]
	v_add_f32_e32 v138, v230, v138
	v_add_f32_e32 v138, v224, v138
	v_add_f32_e32 v223, v225, v138
	v_cvt_pk_bf16_f32 v164, v164, v165
	v_cvt_pk_bf16_f32 v165, v195, v213
	v_exp_f32_e32 v195, v142
	s_waitcnt lgkmcnt(0)
	v_mfma_f32_32x32x16_bf16 v[66:81], v[180:183], v[152:155], v[66:81]
	v_exp_f32_e32 v213, v143
	v_exp_f32_e32 v180, v144
	ds_read_b64_tr_b16 v[138:139], v193 offset:30720
	ds_read_b64_tr_b16 v[140:141], v193 offset:31232
	v_exp_f32_e32 v181, v145
	ds_read_b128 v[216:219], v194 offset:4096
	v_add_f32_e32 v142, v195, v223
	v_mfma_f32_32x32x16_bf16 v[2:17], v[168:171], v[130:133], v[2:17]
	v_add_f32_e32 v142, v213, v142
	v_add_f32_e32 v142, v180, v142
	v_add_f32_e32 v182, v181, v142
	v_cvt_pk_bf16_f32 v166, v229, v220
	v_cvt_pk_bf16_f32 v167, v221, v222
	s_waitcnt lgkmcnt(0)
	v_mfma_f32_32x32x16_bf16 v[98:113], v[216:219], v[156:159], v[98:113]
	v_exp_f32_e32 v183, v114
	ds_read_b64_tr_b16 v[130:131], v193 offset:59392
	ds_read_b64_tr_b16 v[132:133], v193 offset:59904
	v_exp_f32_e32 v220, v115
	ds_read_b128 v[142:145], v194 offset:4608
	v_add_f32_e32 v114, v183, v182
	v_cvt_pk_bf16_f32 v168, v228, v230
	v_mfma_f32_32x32x16_bf16 v[18:33], v[172:175], v[134:137], v[18:33]
	v_add_f32_e32 v114, v220, v114
	v_cvt_pk_bf16_f32 v169, v224, v225
	v_mfma_f32_32x32x16_bf16 v[50:65], v[172:175], v[138:141], v[50:65]
	v_exp_f32_e32 v182, v116
	ds_read_b64_tr_b16 v[134:135], v193 offset:63488
	ds_read_b64_tr_b16 v[136:137], v193 offset:64000
	v_exp_f32_e32 v216, v117
	v_cvt_pk_bf16_f32 v170, v195, v213
	v_add_f32_e32 v114, v182, v114
	v_cvt_pk_bf16_f32 v171, v180, v181
	v_add_f32_e32 v114, v216, v114
	s_waitcnt lgkmcnt(2)
	v_mfma_f32_32x32x16_bf16 v[66:81], v[142:145], v[156:159], v[66:81]
	v_exp_f32_e32 v142, v118
	ds_read_b64_tr_b16 v[138:139], v193 offset:27648
	ds_read_b64_tr_b16 v[140:141], v193 offset:28160
	v_exp_f32_e32 v143, v119
	ds_read_b128 v[116:119], v194 offset:6144
	v_add_f32_e32 v114, v142, v114
	v_add_f32_e32 v114, v143, v114
	v_mfma_f32_32x32x16_bf16 v[34:49], v[172:175], v[130:133], v[34:49]
	s_waitcnt lgkmcnt(3)
	v_mfma_f32_32x32x16_bf16 v[2:17], v[172:175], v[134:137], v[2:17]
	v_exp_f32_e32 v144, v120
	ds_read_b64_tr_b16 v[130:131], v193 offset:31744
	ds_read_b64_tr_b16 v[132:133], v193 offset:32256
	v_exp_f32_e32 v145, v121
	v_add_f32_e32 v114, v144, v114
	v_add_f32_e32 v172, v145, v114
	s_waitcnt lgkmcnt(2)
	v_mfma_f32_32x32x16_bf16 v[98:113], v[116:119], v[160:163], v[98:113]
	v_exp_f32_e32 v114, v122
	ds_read_b64_tr_b16 v[134:135], v193 offset:60416
	ds_read_b64_tr_b16 v[136:137], v193 offset:60928
	v_exp_f32_e32 v115, v123
	ds_read_b128 v[118:121], v194 offset:6656
	v_add_f32_e32 v116, v114, v172
	v_cvt_pk_bf16_f32 v172, v183, v220
	v_mfma_f32_32x32x16_bf16 v[18:33], v[176:179], v[138:141], v[18:33]
	v_add_f32_e32 v180, v115, v116
	v_cvt_pk_bf16_f32 v173, v182, v216
	s_waitcnt lgkmcnt(3)
	v_mfma_f32_32x32x16_bf16 v[50:65], v[176:179], v[130:133], v[50:65]
	v_exp_f32_e32 v116, v124
	v_exp_f32_e32 v117, v125
	ds_read_b64_tr_b16 v[122:123], v193 offset:64512
	ds_read_b64_tr_b16 v[124:125], v193 offset:65024
	v_cvt_pk_bf16_f32 v174, v142, v143
	v_add_f32_e32 v138, v116, v180
	v_add_f32_e32 v138, v117, v138
	v_cvt_pk_bf16_f32 v175, v144, v145
	s_waitcnt lgkmcnt(2)
	v_mfma_f32_32x32x16_bf16 v[66:81], v[118:121], v[160:163], v[66:81]
	v_exp_f32_e32 v118, v126
	v_exp_f32_e32 v119, v127
	v_add_f32_e32 v120, v118, v138
	v_add_f32_e32 v126, v119, v120
	v_mfma_f32_32x32x16_bf16 v[34:49], v[176:179], v[134:137], v[34:49]
	s_waitcnt lgkmcnt(0)
	v_mfma_f32_32x32x16_bf16 v[2:17], v[176:179], v[122:125], v[2:17]
	v_exp_f32_e32 v120, v128
	v_exp_f32_e32 v121, v129
	v_add_f32_e32 v122, v120, v126
	v_add_f32_e32 v122, v121, v122
	s_andn2_b64 vcc, exec, s[4:5]
	s_cbranch_vccnz .LBB0_808
	s_waitcnt lgkmcnt(0)
	ds_read_b128 v[124:127], v215 offset:96
	ds_read_b128 v[128:131], v215 offset:64
	ds_read_b128 v[132:135], v215
	ds_read_b128 v[136:139], v215 offset:32
	s_waitcnt lgkmcnt(0)
	s_waitcnt lgkmcnt(3)
	v_pk_mul_f32 v[32:33], v[32:33], v[126:127]
	v_pk_mul_f32 v[30:31], v[30:31], v[124:125]
	s_waitcnt lgkmcnt(2)
	v_pk_mul_f32 v[28:29], v[28:29], v[130:131]
	v_pk_mul_f32 v[26:27], v[26:27], v[128:129]
	s_waitcnt lgkmcnt(0)
	v_pk_mul_f32 v[24:25], v[24:25], v[138:139]
	v_pk_mul_f32 v[22:23], v[22:23], v[136:137]
	v_pk_mul_f32 v[20:21], v[20:21], v[134:135]
	v_pk_mul_f32 v[18:19], v[18:19], v[132:133]
	v_pk_mul_f32 v[64:65], v[64:65], v[126:127]
	v_pk_mul_f32 v[62:63], v[62:63], v[124:125]
	v_pk_mul_f32 v[60:61], v[60:61], v[130:131]
	v_pk_mul_f32 v[58:59], v[58:59], v[128:129]
	v_pk_mul_f32 v[56:57], v[56:57], v[138:139]
	v_pk_mul_f32 v[54:55], v[54:55], v[136:137]
	v_pk_mul_f32 v[52:53], v[52:53], v[134:135]
	v_pk_mul_f32 v[50:51], v[50:51], v[132:133]
	v_pk_mul_f32 v[48:49], v[48:49], v[126:127]
	v_pk_mul_f32 v[46:47], v[46:47], v[124:125]
	v_pk_mul_f32 v[44:45], v[44:45], v[130:131]
	v_pk_mul_f32 v[42:43], v[42:43], v[128:129]
	v_pk_mul_f32 v[40:41], v[40:41], v[138:139]
	v_pk_mul_f32 v[38:39], v[38:39], v[136:137]
	v_pk_mul_f32 v[36:37], v[36:37], v[134:135]
	v_pk_mul_f32 v[34:35], v[34:35], v[132:133]
	v_pk_mul_f32 v[16:17], v[16:17], v[126:127]
	v_pk_mul_f32 v[14:15], v[14:15], v[124:125]
	v_pk_mul_f32 v[12:13], v[12:13], v[130:131]
	v_pk_mul_f32 v[10:11], v[10:11], v[128:129]
	v_pk_mul_f32 v[8:9], v[8:9], v[138:139]
	v_pk_mul_f32 v[6:7], v[6:7], v[136:137]
	v_pk_mul_f32 v[4:5], v[4:5], v[134:135]
	v_pk_mul_f32 v[2:3], v[2:3], v[132:133]

.LBB0_826:
	s_mov_b64 s[22:23], s[0:1]
	s_waitcnt vmcnt(0) lgkmcnt(0)
	s_barrier
	s_load_dwordx2 s[22:23], s[22:23], 0xa0
	s_lshl_b64 s[4:5], s[62:63], 23
	s_lshl_b64 s[92:93], s[4:5], 1
	v_lshlrev_b32_e32 v83, 10, v207
	v_lshlrev_b32_e32 v82, 10, v211
	s_waitcnt lgkmcnt(0)
	s_add_u32 s4, s22, s92
	s_addc_u32 s5, s23, s93
	s_add_u32 s4, s4, s64
	v_lshlrev_b32_e32 v84, 1, v83
	v_mov_b32_e32 v85, v146
	s_addc_u32 s5, s5, s65
	v_lshlrev_b32_e32 v82, 1, v82
	v_mov_b32_e32 v83, v146
	s_ashr_i32 s61, s60, 31
	v_lshl_add_u64 v[84:85], s[4:5], 0, v[84:85]
	v_lshl_add_u64 v[82:83], s[4:5], 0, v[82:83]
	s_lshl_b64 s[4:5], s[60:61], 8
	s_add_u32 s61, s4, s86
	s_addc_u32 s63, s5, s87
	s_add_u32 s4, s61, s13
	s_addc_u32 s5, s63, s24
	s_lshl_b64 s[4:5], s[4:5], 11
	s_add_u32 s4, s22, s4
	v_lshl_add_u64 v[84:85], s[88:89], 1, v[84:85]
	s_mov_b64 s[28:29], 0x8800080
	v_lshl_add_u64 v[82:83], s[90:91], 1, v[82:83]
	v_mov_b32_e32 v187, v146
	s_addc_u32 s5, s23, s5
	v_lshl_add_u64 v[86:87], v[84:85], 0, s[28:29]
	v_lshl_add_u64 v[82:83], v[82:83], 0, v[186:187]
	s_add_u32 s4, s4, s64
	s_mov_b32 s9, m0
	s_mov_b32 m0, s56
	s_nop 0
	global_load_lds_dwordx4 v[86:87], off
	s_mov_b32 m0, s9
	v_lshl_add_u64 v[88:89], v[82:83], 0, s[58:59]
	s_addc_u32 s5, s5, s65
	s_mov_b32 s9, m0
	s_mov_b32 m0, s55
	s_nop 0
	global_load_lds_dwordx4 v[88:89], off
	s_mov_b32 m0, s9
	s_mov_b64 s[22:23], 0xc800080
	v_lshl_add_u64 v[86:87], v[82:83], 0, s[22:23]
	s_mov_b32 s9, m0
	s_mov_b32 m0, s54
	s_nop 0
	global_load_lds_dwordx4 v[86:87], off
	s_mov_b32 m0, s9
	s_cmp_lg_u32 0, -1
	s_mov_b64 s[22:23], 0x8820080
	s_cselect_b32 s9, 0, 0
	v_lshl_add_u64 v[86:87], v[84:85], 0, s[22:23]
	s_add_i32 s9, s9, s25
	s_mov_b64 s[22:23], 0xc820000
	s_add_i32 s13, s9, 0x2000
	s_mov_b32 s14, m0
	s_mov_b32 m0, s13
	s_nop 0
	global_load_lds_dwordx4 v[86:87], off
	s_mov_b32 m0, s14
	v_lshl_add_u64 v[86:87], v[82:83], 0, s[22:23]
	s_mov_b64 s[22:23], 0xc820080
	s_add_i32 s13, s9, 0x8000
	s_mov_b32 s14, m0
	s_mov_b32 m0, s13
	s_nop 0
	global_load_lds_dwordx4 v[86:87], off
	s_mov_b32 m0, s14
	v_lshl_add_u64 v[82:83], v[82:83], 0, s[22:23]
	s_mov_b64 s[22:23], 0x8840080
	s_add_i32 s13, s9, 0x10000
	s_mov_b32 s14, m0
	s_mov_b32 m0, s13
	s_nop 0
	global_load_lds_dwordx4 v[82:83], off
	s_mov_b32 m0, s14
	v_lshl_add_u64 v[82:83], v[84:85], 0, s[22:23]
	v_mov_b32_e32 v185, v146
	s_addk_i32 s9, 0x4000
	s_mov_b32 s13, m0
	s_mov_b32 m0, s9
	s_nop 0
	global_load_lds_dwordx4 v[82:83], off
	s_mov_b32 m0, s13
	v_lshl_add_u64 v[82:83], s[4:5], 0, v[184:185]
	v_lshl_add_u64 v[82:83], v[82:83], 0, s[30:31]
	global_load_dwordx4 v[148:151], v[82:83], off offset:128
	global_load_dwordx4 v[152:155], v[82:83], off offset:160
	global_load_dwordx4 v[156:159], v[82:83], off offset:192
	global_load_dwordx4 v[160:163], v[82:83], off offset:224
	v_add_u32_e32 v122, s8, v147
	ds_read_b64_tr_b16 v[82:83], v122 offset:24576
	ds_read_b64_tr_b16 v[84:85], v122 offset:25088
	ds_read_b64_tr_b16 v[86:87], v122 offset:28672
	ds_read_b64_tr_b16 v[88:89], v122 offset:29184
	s_waitcnt lgkmcnt(2)
	v_mfma_f32_32x32x16_bf16 v[18:33], v[164:167], v[82:85], v[18:33]
	ds_read_b64_tr_b16 v[90:91], v122 offset:57344
	ds_read_b64_tr_b16 v[92:93], v122 offset:57856
	s_waitcnt lgkmcnt(2)
	v_mfma_f32_32x32x16_bf16 v[50:65], v[164:167], v[86:89], v[50:65]
	ds_read_b64_tr_b16 v[82:83], v122 offset:61440
	ds_read_b64_tr_b16 v[84:85], v122 offset:61952
	s_waitcnt lgkmcnt(2)
	v_mfma_f32_32x32x16_bf16 v[34:49], v[164:167], v[90:93], v[34:49]
	ds_read_b64_tr_b16 v[118:119], v122 offset:25600
	ds_read_b64_tr_b16 v[120:121], v122 offset:26112
	s_waitcnt lgkmcnt(2)
	v_mfma_f32_32x32x16_bf16 v[2:17], v[164:167], v[82:85], v[2:17]
	ds_read_b64_tr_b16 v[114:115], v122 offset:29696
	ds_read_b64_tr_b16 v[116:117], v122 offset:30208
	v_max_f32_e32 v82, v98, v99
	v_max3_f32 v83, v100, v101, v67
	v_max3_f32 v82, v82, v66, v68
	v_max3_f32 v82, v82, v69, v102
	v_max3_f32 v83, v83, v104, v105
	v_max3_f32 v82, v82, v103, v70
	v_max3_f32 v83, v83, v72, v73
	v_max3_f32 v82, v82, v71, v106
	v_max3_f32 v83, v83, v108, v109
	v_max3_f32 v82, v82, v107, v74
	v_max3_f32 v83, v83, v76, v77
	v_max3_f32 v82, v82, v75, v110
	v_max3_f32 v83, v83, v112, v113
	v_max3_f32 v82, v82, v111, v78
	v_max3_f32 v83, v83, v80, v81
	v_max3_f32 v82, v82, v79, v83
	v_mov_b32_e32 v83, v82
	s_nop 1
	v_permlane32_swap_b32_e32 v82, v83
	v_max_f32_e32 v82, v82, v83
	v_cmp_lt_f32_e32 vcc, s15, v82
	s_cmp_lg_u64 vcc, 0
	s_cselect_b64 s[8:9], -1, 0
	s_cbranch_vccz .LBB0_830
	v_max_f32_e32 v82, v82, v82
	v_max_f32_e32 v123, 0, v82
	v_add_f32_e32 v82, v212, v123
	v_xor_b32_e32 v82, 0x80000000, v82
	v_mov_b32_e32 v83, v82
	v_mov_b32_e32 v84, v82
	v_mov_b32_e32 v85, v82
	v_mov_b32_e32 v86, v82
	v_mov_b32_e32 v87, v82
	v_mov_b32_e32 v88, v82
	v_mov_b32_e32 v89, v82
	v_mov_b32_e32 v90, v82
	v_mov_b32_e32 v91, v82
	v_mov_b32_e32 v92, v82
	v_mov_b32_e32 v93, v82
	v_mov_b32_e32 v94, v82
	v_mov_b32_e32 v95, v82
	v_mov_b32_e32 v96, v82
	v_mov_b32_e32 v97, v82
	v_cmp_gt_u32_e32 vcc, 32, v207
	v_exp_f32_e64 v82, -v123
	s_and_saveexec_b64 s[4:5], vcc
	s_mov_b64 s[86:87], 0x14800000
	ds_write_b32 v1, v82
	s_or_b64 exec, exec, s[4:5]
	v_sub_f32_e32 v113, v113, v123
	v_sub_f32_e32 v112, v112, v123
	v_sub_f32_e32 v111, v111, v123
	v_sub_f32_e32 v110, v110, v123
	v_sub_f32_e32 v109, v109, v123
	v_sub_f32_e32 v108, v108, v123
	v_sub_f32_e32 v107, v107, v123
	v_sub_f32_e32 v106, v106, v123
	v_sub_f32_e32 v105, v105, v123
	v_sub_f32_e32 v104, v104, v123
	v_sub_f32_e32 v103, v103, v123
	v_sub_f32_e32 v102, v102, v123
	v_sub_f32_e32 v101, v101, v123
	v_sub_f32_e32 v100, v100, v123
	v_sub_f32_e32 v99, v99, v123
	v_sub_f32_e32 v98, v98, v123
	v_sub_f32_e32 v81, v81, v123
	v_sub_f32_e32 v80, v80, v123
	v_sub_f32_e32 v79, v79, v123
	v_sub_f32_e32 v78, v78, v123
	v_sub_f32_e32 v77, v77, v123
	v_sub_f32_e32 v76, v76, v123
	v_sub_f32_e32 v75, v75, v123
	v_sub_f32_e32 v74, v74, v123
	v_sub_f32_e32 v73, v73, v123
	v_sub_f32_e32 v72, v72, v123
	v_sub_f32_e32 v71, v71, v123
	v_sub_f32_e32 v70, v70, v123
	v_sub_f32_e32 v69, v69, v123
	v_sub_f32_e32 v68, v68, v123
	v_sub_f32_e32 v67, v67, v123
	v_sub_f32_e32 v66, v66, v123
	v_mul_f32_e32 v213, v213, v82
	s_branch .LBB0_831

.LBB0_831:
	s_waitcnt lgkmcnt(2)
	v_mfma_f32_32x32x16_bf16 v[18:33], v[168:171], v[118:121], v[18:33]
	v_exp_f32_e32 v94, v98
	v_exp_f32_e32 v95, v99
	v_exp_f32_e32 v96, v100
	ds_read_b64_tr_b16 v[82:83], v122 offset:58368
	ds_read_b64_tr_b16 v[84:85], v122 offset:58880
	v_exp_f32_e32 v97, v101
	v_add_f32_e32 v86, v95, v94
	v_add_f32_e32 v86, v96, v86
	v_add_f32_e32 v90, v97, v86
	s_waitcnt lgkmcnt(2)
	v_mfma_f32_32x32x16_bf16 v[50:65], v[168:171], v[114:117], v[50:65]
	v_exp_f32_e32 v98, v102
	v_exp_f32_e32 v99, v103
	v_exp_f32_e32 v100, v104
	ds_read_b64_tr_b16 v[86:87], v122 offset:62464
	ds_read_b64_tr_b16 v[88:89], v122 offset:62976
	v_exp_f32_e32 v101, v105
	v_add_f32_e32 v90, v98, v90
	v_add_f32_e32 v90, v99, v90
	v_add_f32_e32 v90, v100, v90
	v_add_f32_e32 v102, v101, v90
	s_waitcnt lgkmcnt(2)
	v_mfma_f32_32x32x16_bf16 v[34:49], v[168:171], v[82:85], v[34:49]
	v_exp_f32_e32 v103, v106
	v_exp_f32_e32 v104, v107
	v_exp_f32_e32 v105, v108
	ds_read_b64_tr_b16 v[90:91], v122 offset:26624
	ds_read_b64_tr_b16 v[92:93], v122 offset:27136
	v_exp_f32_e32 v106, v109
	v_add_f32_e32 v82, v103, v102
	v_add_f32_e32 v82, v104, v82
	v_add_f32_e32 v82, v105, v82
	v_add_f32_e32 v102, v106, v82
	v_cvt_pk_bf16_f32 v164, v94, v95
	v_cvt_pk_bf16_f32 v165, v96, v97
	s_waitcnt lgkmcnt(2)
	v_mfma_f32_32x32x16_bf16 v[2:17], v[168:171], v[86:89], v[2:17]
	v_exp_f32_e32 v94, v110
	v_exp_f32_e32 v95, v111
	v_exp_f32_e32 v96, v112
	ds_read_b64_tr_b16 v[82:83], v122 offset:30720
	ds_read_b64_tr_b16 v[84:85], v122 offset:31232
	v_exp_f32_e32 v97, v113
	v_add_f32_e32 v86, v94, v102
	v_add_f32_e32 v86, v95, v86
	v_add_f32_e32 v86, v96, v86
	v_add_f32_e32 v102, v97, v86
	v_cvt_pk_bf16_f32 v166, v98, v99
	v_cvt_pk_bf16_f32 v167, v100, v101
	s_waitcnt lgkmcnt(2)
	v_mfma_f32_32x32x16_bf16 v[18:33], v[172:175], v[90:93], v[18:33]
	v_exp_f32_e32 v98, v66
	ds_read_b64_tr_b16 v[86:87], v122 offset:59392
	ds_read_b64_tr_b16 v[88:89], v122 offset:59904
	v_exp_f32_e32 v99, v67
	v_cvt_pk_bf16_f32 v168, v103, v104
	v_add_f32_e32 v66, v98, v102
	v_cvt_pk_bf16_f32 v169, v105, v106
	v_add_f32_e32 v66, v99, v66
	s_waitcnt lgkmcnt(2)
	v_mfma_f32_32x32x16_bf16 v[50:65], v[172:175], v[82:85], v[50:65]
	v_exp_f32_e32 v100, v68
	ds_read_b64_tr_b16 v[90:91], v122 offset:63488
	ds_read_b64_tr_b16 v[92:93], v122 offset:64000
	v_exp_f32_e32 v101, v69
	v_cvt_pk_bf16_f32 v170, v94, v95
	v_add_f32_e32 v66, v100, v66
	v_cvt_pk_bf16_f32 v171, v96, v97
	v_add_f32_e32 v82, v101, v66
	s_waitcnt lgkmcnt(2)
	v_mfma_f32_32x32x16_bf16 v[34:49], v[172:175], v[86:89], v[34:49]
	v_exp_f32_e32 v94, v70
	ds_read_b64_tr_b16 v[66:67], v122 offset:27648
	ds_read_b64_tr_b16 v[68:69], v122 offset:28160
	v_exp_f32_e32 v95, v71
	v_add_f32_e32 v70, v94, v82
	v_add_f32_e32 v70, v95, v70
	s_waitcnt lgkmcnt(2)
	v_mfma_f32_32x32x16_bf16 v[2:17], v[172:175], v[90:93], v[2:17]
	v_exp_f32_e32 v72, v72
	ds_read_b64_tr_b16 v[82:83], v122 offset:31744
	ds_read_b64_tr_b16 v[84:85], v122 offset:32256
	v_exp_f32_e32 v73, v73
	v_add_f32_e32 v70, v72, v70
	v_add_f32_e32 v70, v73, v70
	s_waitcnt lgkmcnt(2)
	v_mfma_f32_32x32x16_bf16 v[18:33], v[176:179], v[66:69], v[18:33]
	v_exp_f32_e32 v68, v74
	ds_read_b64_tr_b16 v[86:87], v122 offset:60416
	ds_read_b64_tr_b16 v[88:89], v122 offset:60928
	v_exp_f32_e32 v69, v75
	v_cvt_pk_bf16_f32 v172, v98, v99
	v_add_f32_e32 v66, v68, v70
	v_cvt_pk_bf16_f32 v173, v100, v101
	v_add_f32_e32 v66, v69, v66
	s_waitcnt lgkmcnt(2)
	v_mfma_f32_32x32x16_bf16 v[50:65], v[176:179], v[82:85], v[50:65]
	v_exp_f32_e32 v70, v76
	v_exp_f32_e32 v71, v77
	ds_read_b64_tr_b16 v[74:75], v122 offset:64512
	ds_read_b64_tr_b16 v[76:77], v122 offset:65024
	v_cvt_pk_bf16_f32 v174, v94, v95
	v_add_f32_e32 v66, v70, v66
	v_add_f32_e32 v66, v71, v66
	v_cvt_pk_bf16_f32 v175, v72, v73
	s_waitcnt lgkmcnt(2)
	v_mfma_f32_32x32x16_bf16 v[34:49], v[176:179], v[86:89], v[34:49]
	v_exp_f32_e32 v72, v78
	v_exp_f32_e32 v73, v79
	v_add_f32_e32 v66, v72, v66
	v_add_f32_e32 v66, v73, v66
	s_waitcnt lgkmcnt(0)
	v_mfma_f32_32x32x16_bf16 v[2:17], v[176:179], v[74:77], v[2:17]
	v_exp_f32_e32 v74, v80
	v_exp_f32_e32 v75, v81
	v_add_f32_e32 v66, v74, v66
	v_add_f32_e32 v67, v75, v66
	s_andn2_b64 vcc, exec, s[8:9]
	v_lshl_add_u32 v66, v209, 4, s57
	s_cbranch_vccnz .LBB0_833
	s_waitcnt lgkmcnt(0)
	ds_read_b128 v[76:79], v66 offset:96
	ds_read_b128 v[80:83], v66 offset:64
	ds_read_b128 v[84:87], v66 offset:32
	ds_read_b128 v[88:91], v66
	s_waitcnt lgkmcnt(0)
	s_waitcnt lgkmcnt(3)
	v_pk_mul_f32 v[32:33], v[32:33], v[78:79]
	s_waitcnt lgkmcnt(2)
	v_pk_mul_f32 v[28:29], v[28:29], v[82:83]
	s_waitcnt lgkmcnt(1)
	v_pk_mul_f32 v[24:25], v[24:25], v[86:87]
	s_waitcnt lgkmcnt(0)
	v_pk_mul_f32 v[20:21], v[20:21], v[90:91]
	v_pk_mul_f32 v[30:31], v[30:31], v[76:77]
	v_pk_mul_f32 v[26:27], v[26:27], v[80:81]
	v_pk_mul_f32 v[22:23], v[22:23], v[84:85]
	v_pk_mul_f32 v[18:19], v[18:19], v[88:89]
	v_pk_mul_f32 v[64:65], v[64:65], v[78:79]
	v_pk_mul_f32 v[60:61], v[60:61], v[82:83]
	v_pk_mul_f32 v[56:57], v[56:57], v[86:87]
	v_pk_mul_f32 v[52:53], v[52:53], v[90:91]
	v_pk_mul_f32 v[62:63], v[62:63], v[76:77]
	v_pk_mul_f32 v[58:59], v[58:59], v[80:81]
	v_pk_mul_f32 v[54:55], v[54:55], v[84:85]
	v_pk_mul_f32 v[50:51], v[50:51], v[88:89]
	v_pk_mul_f32 v[48:49], v[48:49], v[78:79]
	v_pk_mul_f32 v[44:45], v[44:45], v[82:83]
	v_pk_mul_f32 v[40:41], v[40:41], v[86:87]
	v_pk_mul_f32 v[36:37], v[36:37], v[90:91]
	v_pk_mul_f32 v[46:47], v[46:47], v[76:77]
	v_pk_mul_f32 v[42:43], v[42:43], v[80:81]
	v_pk_mul_f32 v[38:39], v[38:39], v[84:85]
	v_pk_mul_f32 v[34:35], v[34:35], v[88:89]
	v_pk_mul_f32 v[16:17], v[16:17], v[78:79]
	v_pk_mul_f32 v[12:13], v[12:13], v[82:83]
	v_pk_mul_f32 v[8:9], v[8:9], v[86:87]
	v_pk_mul_f32 v[4:5], v[4:5], v[90:91]
	v_pk_mul_f32 v[14:15], v[14:15], v[76:77]
	v_pk_mul_f32 v[10:11], v[10:11], v[80:81]
	v_pk_mul_f32 v[6:7], v[6:7], v[84:85]
	v_pk_mul_f32 v[2:3], v[2:3], v[88:89]

.LBB0_845:
	ds_read_b128 v[42:45], v40 offset:8192
	v_max_f32_e32 v46, v18, v19
	v_max3_f32 v47, v20, v21, v3
	v_max3_f32 v46, v46, v2, v4
	v_max3_f32 v46, v46, v5, v22
	v_max3_f32 v47, v47, v24, v25
	v_max3_f32 v46, v46, v23, v6
	v_max3_f32 v47, v47, v8, v9
	v_max3_f32 v46, v46, v7, v26
	v_max3_f32 v47, v47, v28, v29
	v_max3_f32 v46, v46, v27, v10
	v_max3_f32 v47, v47, v12, v13
	v_max3_f32 v46, v46, v11, v30
	v_max3_f32 v47, v47, v32, v33
	v_max3_f32 v46, v46, v31, v14
	v_max3_f32 v47, v47, v16, v17
	v_max3_f32 v46, v46, v15, v47
	v_mov_b32_e32 v47, v46
	s_nop 1
	v_permlane32_swap_b32_e32 v46, v47
	v_max_f32_e32 v47, v47, v47
	v_max_f32_e32 v46, v46, v46
	v_max_f32_e32 v210, v46, v47
	v_xor_b32_e32 v82, 0x80000000, v210
	v_sub_f32_e32 v10, v10, v210
	v_mov_b32_e32 v83, v82
	v_mov_b32_e32 v84, v82
	v_mov_b32_e32 v85, v82
	v_mov_b32_e32 v86, v82
	v_mov_b32_e32 v87, v82
	v_mov_b32_e32 v88, v82
	v_mov_b32_e32 v89, v82
	v_mov_b32_e32 v90, v82
	v_mov_b32_e32 v91, v82
	v_mov_b32_e32 v92, v82
	v_mov_b32_e32 v93, v82
	v_mov_b32_e32 v94, v82
	v_mov_b32_e32 v95, v82
	v_mov_b32_e32 v96, v82
	v_mov_b32_e32 v97, v82
	v_sub_f32_e32 v18, v18, v210
	v_sub_f32_e32 v46, v2, v210
	v_sub_f32_e32 v19, v19, v210
	v_sub_f32_e32 v47, v3, v210
	v_sub_f32_e32 v20, v20, v210
	v_sub_f32_e32 v48, v4, v210
	v_sub_f32_e32 v21, v21, v210
	v_sub_f32_e32 v49, v5, v210
	v_sub_f32_e32 v22, v22, v210
	v_sub_f32_e32 v50, v6, v210
	v_sub_f32_e32 v23, v23, v210
	v_sub_f32_e32 v51, v7, v210
	v_sub_f32_e32 v24, v24, v210
	v_sub_f32_e32 v52, v8, v210
	v_sub_f32_e32 v25, v25, v210
	v_sub_f32_e32 v53, v9, v210
	v_sub_f32_e32 v26, v26, v210
	v_sub_f32_e32 v27, v27, v210
	v_sub_f32_e32 v11, v11, v210
	v_sub_f32_e32 v28, v28, v210
	v_sub_f32_e32 v54, v12, v210
	v_sub_f32_e32 v12, v29, v210
	v_sub_f32_e32 v29, v13, v210
	v_sub_f32_e32 v13, v30, v210
	v_sub_f32_e32 v14, v14, v210
	v_sub_f32_e32 v30, v31, v210
	v_sub_f32_e32 v15, v15, v210
	v_sub_f32_e32 v31, v32, v210
	v_sub_f32_e32 v16, v16, v210
	v_sub_f32_e32 v32, v33, v210
	v_sub_f32_e32 v17, v17, v210
	s_waitcnt lgkmcnt(0)
	v_mfma_f32_32x32x16_bf16 v[98:113], v[42:45], v[148:151], v[82:97]
	v_exp_f32_e32 v18, v18
	v_exp_f32_e32 v19, v19
	v_exp_f32_e32 v20, v20
	ds_read_b128 v[2:5], v40 offset:8704
	v_exp_f32_e32 v21, v21
	v_add_f32_e32 v6, v19, v18
	v_add_f32_e32 v6, v20, v6
	v_add_f32_e32 v33, v21, v6
	v_exp_f32_e32 v22, v22
	s_waitcnt lgkmcnt(0)
	v_mfma_f32_32x32x16_bf16 v[66:81], v[2:5], v[148:151], v[82:97]
	v_exp_f32_e32 v23, v23
	v_exp_f32_e32 v24, v24
	ds_read_b128 v[6:9], v40 offset:10240
	v_exp_f32_e32 v25, v25
	v_add_f32_e32 v33, v33, v22
	v_add_f32_e32 v2, v23, v33
	v_add_f32_e32 v2, v24, v2
	v_add_f32_e32 v33, v25, v2
	s_waitcnt lgkmcnt(0)
	v_mfma_f32_32x32x16_bf16 v[98:113], v[6:9], v[152:155], v[98:113]
	v_exp_f32_e32 v26, v26
	v_exp_f32_e32 v27, v27
	v_exp_f32_e32 v28, v28
	ds_read_b128 v[2:5], v40 offset:10752
	v_exp_f32_e32 v12, v12
	v_add_f32_e32 v6, v26, v33
	v_add_f32_e32 v6, v27, v6
	v_mov_b32_e32 v147, v146
	v_add_f32_e32 v6, v28, v6
	v_cvt_pk_bf16_f32 v144, v18, v19
	v_cvt_pk_bf16_f32 v145, v20, v21
	v_mov_b64_e32 v[166:167], v[146:147]
	v_add_f32_e32 v33, v12, v6
	v_mov_b64_e32 v[164:165], v[144:145]
	s_waitcnt lgkmcnt(0)
	v_mfma_f32_32x32x16_bf16 v[66:81], v[2:5], v[152:155], v[66:81]
	v_exp_f32_e32 v13, v13
	v_exp_f32_e32 v18, v30
	v_exp_f32_e32 v19, v31
	ds_read_b128 v[6:9], v40 offset:12288
	v_exp_f32_e32 v20, v32
	v_add_f32_e32 v2, v13, v33
	v_add_f32_e32 v2, v18, v2
	v_add_f32_e32 v2, v19, v2
	v_add_f32_e32 v21, v20, v2
	v_cvt_pk_bf16_f32 v166, v22, v23
	v_cvt_pk_bf16_f32 v167, v24, v25
	s_waitcnt lgkmcnt(0)
	v_mfma_f32_32x32x16_bf16 v[98:113], v[6:9], v[156:159], v[98:113]
	v_exp_f32_e32 v22, v46
	ds_read_b128 v[2:5], v40 offset:12800
	v_exp_f32_e32 v23, v47
	v_cvt_pk_bf16_f32 v168, v26, v27
	v_add_f32_e32 v6, v22, v21
	v_cvt_pk_bf16_f32 v169, v28, v12
	v_add_f32_e32 v6, v23, v6
	v_exp_f32_e32 v21, v48
	v_exp_f32_e32 v24, v49
	v_cvt_pk_bf16_f32 v170, v13, v18
	v_cvt_pk_bf16_f32 v171, v19, v20
	v_add_f32_e32 v6, v21, v6
	v_add_f32_e32 v12, v24, v6
	s_waitcnt lgkmcnt(0)
	v_mfma_f32_32x32x16_bf16 v[66:81], v[2:5], v[156:159], v[66:81]
	v_exp_f32_e32 v18, v50
	ds_read_b128 v[6:9], v40 offset:14336
	v_exp_f32_e32 v19, v51
	v_add_f32_e32 v2, v18, v12
	v_add_f32_e32 v2, v19, v2
	v_exp_f32_e32 v20, v52
	v_exp_f32_e32 v25, v53
	v_add_f32_e32 v2, v20, v2
	v_add_f32_e32 v4, v25, v2
	s_waitcnt lgkmcnt(0)
	v_mfma_f32_32x32x16_bf16 v[98:113], v[6:9], v[160:163], v[98:113]
	v_exp_f32_e32 v2, v10
	v_exp_f32_e32 v3, v11
	ds_read_b128 v[10:13], v40 offset:14848
	v_cvt_pk_bf16_f32 v172, v22, v23
	v_add_f32_e32 v4, v2, v4
	v_add_f32_e32 v26, v3, v4
	v_cvt_pk_bf16_f32 v173, v21, v24
	v_exp_f32_e32 v4, v54
	v_exp_f32_e32 v5, v29
	v_cvt_pk_bf16_f32 v174, v18, v19
	v_cvt_pk_bf16_f32 v175, v20, v25
	v_add_f32_e32 v6, v4, v26
	v_add_f32_e32 v8, v5, v6
	s_waitcnt lgkmcnt(0)
	v_mfma_f32_32x32x16_bf16 v[66:81], v[10:13], v[160:163], v[66:81]
	v_exp_f32_e32 v6, v14
	v_exp_f32_e32 v7, v15
	v_add_f32_e32 v8, v6, v8
	v_add_f32_e32 v8, v7, v8
	v_exp_f32_e32 v9, v16
	v_exp_f32_e32 v10, v17
	v_add_f32_e32 v8, v9, v8
	v_add_f32_e32 v8, v10, v8
	s_andn2_b64 vcc, exec, s[76:77]
	s_cbranch_vccnz .LBB0_847
	v_or_b32_e32 v12, 0x60, v38
	v_or_b32_e32 v11, 64, v38
	v_cmp_le_i32_e32 vcc, v12, v212
	s_nop 1
	v_cndmask_b32_e32 v66, v206, v66, vcc
	v_cmp_lt_i32_e32 vcc, v11, v212
	s_nop 1
	v_cndmask_b32_e32 v99, v206, v99, vcc
	v_cmp_le_i32_e32 vcc, v11, v212
	v_or_b32_e32 v11, 0x61, v38
	s_nop 0
	v_cndmask_b32_e32 v98, v206, v98, vcc
	v_cmp_le_i32_e32 vcc, v11, v212
	v_or_b32_e32 v11, 0x42, v38
	s_nop 0
	v_cndmask_b32_e32 v67, v206, v67, vcc
	v_cmp_le_i32_e32 vcc, v11, v212
	v_or_b32_e32 v11, 0x62, v38
	s_nop 0
	v_cndmask_b32_e32 v100, v206, v100, vcc
	v_cmp_le_i32_e32 vcc, v11, v212
	v_or_b32_e32 v11, 0x43, v38
	s_nop 0
	v_cndmask_b32_e32 v68, v206, v68, vcc
	v_cmp_le_i32_e32 vcc, v11, v212
	v_or_b32_e32 v11, 0x63, v38
	s_nop 0
	v_cndmask_b32_e32 v101, v206, v101, vcc
	v_cmp_le_i32_e32 vcc, v11, v212
	v_or_b32_e32 v11, 0x48, v38
	s_nop 0
	v_cndmask_b32_e32 v69, v206, v69, vcc
	v_cmp_le_i32_e32 vcc, v11, v212
	v_or_b32_e32 v11, 0x68, v38
	s_nop 0
	v_cndmask_b32_e32 v102, v206, v102, vcc
	v_cmp_le_i32_e32 vcc, v11, v212
	v_or_b32_e32 v11, 0x49, v38
	s_nop 0
	v_cndmask_b32_e32 v70, v206, v70, vcc
	v_cmp_le_i32_e32 vcc, v11, v212
	v_or_b32_e32 v11, 0x69, v38
	s_nop 0
	v_cndmask_b32_e32 v103, v206, v103, vcc
	v_cmp_le_i32_e32 vcc, v11, v212
	v_or_b32_e32 v11, 0x4a, v38
	s_nop 0
	v_cndmask_b32_e32 v71, v206, v71, vcc
	v_cmp_le_i32_e32 vcc, v11, v212
	v_or_b32_e32 v11, 0x6a, v38
	s_nop 0
	v_cndmask_b32_e32 v104, v206, v104, vcc
	v_cmp_le_i32_e32 vcc, v11, v212
	v_or_b32_e32 v11, 0x4b, v38
	s_nop 0
	v_cndmask_b32_e32 v72, v206, v72, vcc
	v_cmp_le_i32_e32 vcc, v11, v212
	v_or_b32_e32 v11, 0x6b, v38
	s_nop 0
	v_cndmask_b32_e32 v105, v206, v105, vcc
	v_cmp_le_i32_e32 vcc, v11, v212
	v_or_b32_e32 v11, 0x50, v38
	s_nop 0
	v_cndmask_b32_e32 v73, v206, v73, vcc
	v_cmp_le_i32_e32 vcc, v11, v212
	v_or_b32_e32 v11, 0x70, v38
	s_nop 0
	v_cndmask_b32_e32 v106, v206, v106, vcc
	v_cmp_le_i32_e32 vcc, v11, v212
	v_or_b32_e32 v11, 0x51, v38
	s_nop 0
	v_cndmask_b32_e32 v74, v206, v74, vcc
	v_cmp_le_i32_e32 vcc, v11, v212
	v_or_b32_e32 v11, 0x71, v38
	s_nop 0
	v_cndmask_b32_e32 v107, v206, v107, vcc
	v_cmp_le_i32_e32 vcc, v11, v212
	v_or_b32_e32 v11, 0x52, v38
	s_nop 0
	v_cndmask_b32_e32 v75, v206, v75, vcc
	v_cmp_le_i32_e32 vcc, v11, v212
	v_or_b32_e32 v11, 0x72, v38
	s_nop 0
	v_cndmask_b32_e32 v108, v206, v108, vcc
	v_cmp_le_i32_e32 vcc, v11, v212
	v_or_b32_e32 v11, 0x53, v38
	s_nop 0
	v_cndmask_b32_e32 v76, v206, v76, vcc
	v_cmp_le_i32_e32 vcc, v11, v212
	v_or_b32_e32 v11, 0x73, v38
	s_nop 0
	v_cndmask_b32_e32 v109, v206, v109, vcc
	v_cmp_le_i32_e32 vcc, v11, v212
	v_or_b32_e32 v11, 0x58, v38
	s_nop 0
	v_cndmask_b32_e32 v77, v206, v77, vcc
	v_cmp_le_i32_e32 vcc, v11, v212
	v_or_b32_e32 v11, 0x78, v38
	s_nop 0
	v_cndmask_b32_e32 v110, v206, v110, vcc
	v_cmp_le_i32_e32 vcc, v11, v212
	v_or_b32_e32 v11, 0x59, v38
	s_nop 0
	v_cndmask_b32_e32 v78, v206, v78, vcc
	v_cmp_le_i32_e32 vcc, v11, v212
	v_or_b32_e32 v11, 0x79, v38
	s_nop 0
	v_cndmask_b32_e32 v111, v206, v111, vcc
	v_cmp_le_i32_e32 vcc, v11, v212
	v_or_b32_e32 v11, 0x5a, v38
	s_nop 0
	v_cndmask_b32_e32 v79, v206, v79, vcc
	v_cmp_le_i32_e32 vcc, v11, v212
	v_or_b32_e32 v11, 0x7a, v38
	s_nop 0
	v_cndmask_b32_e32 v112, v206, v112, vcc
	v_cmp_le_i32_e32 vcc, v11, v212
	v_or_b32_e32 v11, 0x5b, v38
	s_nop 0
	v_cndmask_b32_e32 v80, v206, v80, vcc
	v_cmp_le_i32_e32 vcc, v11, v212
	v_or_b32_e32 v11, 0x7b, v38
	s_nop 0
	v_cndmask_b32_e32 v113, v206, v113, vcc
	v_cmp_le_i32_e32 vcc, v11, v212
	s_nop 1
	v_cndmask_b32_e32 v81, v206, v81, vcc

.LBB0_857:
	s_mul_hi_u32 s4, s56, 0xaaaaaaab
	s_lshr_b32 s50, s4, 1
	s_mul_i32 s4, s50, 0xffffa000
	s_add_i32 s4, s14, s4
	s_and_b32 s51, s14, 0x6000
	v_add_u32_e32 v216, s4, v187
	v_add_u32_e32 v215, s51, v209
	v_add_u32_e32 v216, 0xffffc000, v216
	ds_read_b64_tr_b16 v[118:119], v215 offset:24576
	ds_read_b64_tr_b16 v[120:121], v215 offset:25088
	ds_read_b64_tr_b16 v[122:123], v215 offset:28672
	ds_read_b64_tr_b16 v[124:125], v215 offset:29184
	ds_read_b128 v[114:117], v216
	s_waitcnt lgkmcnt(3)
	v_mfma_f32_32x32x16_bf16 v[18:33], v[164:167], v[118:121], v[18:33]
	ds_read_b64_tr_b16 v[126:127], v215 offset:57344
	ds_read_b64_tr_b16 v[128:129], v215 offset:57856
	s_waitcnt lgkmcnt(3)
	v_mfma_f32_32x32x16_bf16 v[50:65], v[164:167], v[122:125], v[50:65]
	ds_read_b64_tr_b16 v[130:131], v215 offset:61440
	ds_read_b64_tr_b16 v[132:133], v215 offset:61952
	s_waitcnt lgkmcnt(2)
	v_mfma_f32_32x32x16_bf16 v[34:49], v[164:167], v[126:129], v[34:49]
	ds_read_b64_tr_b16 v[118:119], v215 offset:25600
	ds_read_b64_tr_b16 v[120:121], v215 offset:26112
	s_waitcnt lgkmcnt(2)
	v_mfma_f32_32x32x16_bf16 v[2:17], v[164:167], v[130:133], v[2:17]
	ds_read_b64_tr_b16 v[180:181], v215 offset:29696
	ds_read_b64_tr_b16 v[182:183], v215 offset:30208
	v_max_f32_e32 v122, v98, v99
	v_max3_f32 v123, v100, v101, v67
	v_max3_f32 v122, v122, v66, v68
	v_max3_f32 v122, v122, v69, v102
	v_max3_f32 v123, v123, v104, v105
	v_max3_f32 v122, v122, v103, v70
	v_max3_f32 v123, v123, v72, v73
	v_max3_f32 v122, v122, v71, v106
	v_max3_f32 v123, v123, v108, v109
	v_max3_f32 v122, v122, v107, v74
	v_max3_f32 v123, v123, v76, v77
	v_max3_f32 v122, v122, v75, v110
	v_max3_f32 v123, v123, v112, v113
	v_max3_f32 v122, v122, v111, v78
	v_max3_f32 v123, v123, v80, v81
	v_max3_f32 v122, v122, v79, v123
	v_mov_b32_e32 v123, v122
	s_nop 1
	v_permlane32_swap_b32_e32 v122, v123
	v_max_f32_e32 v122, v122, v123
	v_cmp_lt_f32_e32 vcc, s15, v122
	s_cmp_lg_u64 vcc, 0
	s_cselect_b64 s[4:5], -1, 0
	s_cbranch_vccz .LBB0_861
	v_max_f32_e32 v82, v122, v122
	v_max_f32_e32 v122, 0, v82
	v_exp_f32_e64 v123, -v122
	v_add_f32_e32 v210, v210, v122
	v_xor_b32_e32 v82, 0x80000000, v210
	v_mov_b32_e32 v83, v82
	v_mov_b32_e32 v84, v82
	v_mov_b32_e32 v85, v82
	v_mov_b32_e32 v86, v82
	v_mov_b32_e32 v87, v82
	v_mov_b32_e32 v88, v82
	v_mov_b32_e32 v89, v82
	v_mov_b32_e32 v90, v82
	v_mov_b32_e32 v91, v82
	v_mov_b32_e32 v92, v82
	v_mov_b32_e32 v93, v82
	v_mov_b32_e32 v94, v82
	v_mov_b32_e32 v95, v82
	v_mov_b32_e32 v96, v82
	v_mov_b32_e32 v97, v82
	s_and_saveexec_b64 s[82:83], s[6:7]
	ds_write_b32 v147, v123
	s_or_b64 exec, exec, s[82:83]
	v_sub_f32_e32 v113, v113, v122
	v_sub_f32_e32 v112, v112, v122
	v_sub_f32_e32 v111, v111, v122
	v_sub_f32_e32 v110, v110, v122
	v_sub_f32_e32 v109, v109, v122
	v_sub_f32_e32 v108, v108, v122
	v_sub_f32_e32 v107, v107, v122
	v_sub_f32_e32 v106, v106, v122
	v_sub_f32_e32 v105, v105, v122
	v_sub_f32_e32 v104, v104, v122
	v_sub_f32_e32 v103, v103, v122
	v_sub_f32_e32 v102, v102, v122
	v_sub_f32_e32 v101, v101, v122
	v_sub_f32_e32 v100, v100, v122
	v_sub_f32_e32 v99, v99, v122
	v_sub_f32_e32 v98, v98, v122
	v_sub_f32_e32 v81, v81, v122
	v_sub_f32_e32 v80, v80, v122
	v_sub_f32_e32 v79, v79, v122
	v_sub_f32_e32 v78, v78, v122
	v_sub_f32_e32 v77, v77, v122
	v_sub_f32_e32 v76, v76, v122
	v_sub_f32_e32 v75, v75, v122
	v_sub_f32_e32 v74, v74, v122
	v_sub_f32_e32 v73, v73, v122
	v_sub_f32_e32 v72, v72, v122
	v_sub_f32_e32 v71, v71, v122
	v_sub_f32_e32 v70, v70, v122
	v_sub_f32_e32 v69, v69, v122
	v_sub_f32_e32 v68, v68, v122
	v_sub_f32_e32 v67, v67, v122
	v_sub_f32_e32 v66, v66, v122
	v_mul_f32_e32 v213, v213, v123
.LBB0_861:
	v_exp_f32_e32 v164, v98
	v_mfma_f32_32x32x16_bf16 v[130:145], v[114:117], v[148:151], v[82:97]
	v_exp_f32_e32 v165, v99
	v_exp_f32_e32 v217, v100
	ds_read_b64_tr_b16 v[218:219], v215 offset:58368
	ds_read_b64_tr_b16 v[220:221], v215 offset:58880
	v_exp_f32_e32 v230, v101
	ds_read_b128 v[222:225], v216 offset:512
	s_waitcnt lgkmcnt(5)
	v_mfma_f32_32x32x16_bf16 v[18:33], v[168:171], v[118:121], v[18:33]
	v_add_f32_e32 v98, v165, v164
	v_add_f32_e32 v98, v217, v98
	v_add_f32_e32 v231, v230, v98
	ds_read_b64_tr_b16 v[98:99], v215 offset:62464
	ds_read_b64_tr_b16 v[100:101], v215 offset:62976
	ds_read_b128 v[226:229], v216 offset:2048
	v_exp_f32_e32 v232, v102
	s_waitcnt lgkmcnt(3)
	v_mfma_f32_32x32x16_bf16 v[114:129], v[222:225], v[148:151], v[82:97]
	v_exp_f32_e32 v222, v103
	v_exp_f32_e32 v223, v104
	v_exp_f32_e32 v224, v105
	v_add_f32_e32 v102, v232, v231
	v_add_f32_e32 v102, v222, v102
	v_add_f32_e32 v102, v223, v102
	v_add_f32_e32 v225, v224, v102
	v_mfma_f32_32x32x16_bf16 v[50:65], v[168:171], v[180:183], v[50:65]
	v_exp_f32_e32 v231, v106
	s_waitcnt lgkmcnt(0)
	v_mfma_f32_32x32x16_bf16 v[130:145], v[226:229], v[152:155], v[130:145]
	v_exp_f32_e32 v233, v107
	v_exp_f32_e32 v226, v108
	ds_read_b64_tr_b16 v[102:103], v215 offset:26624
	ds_read_b64_tr_b16 v[104:105], v215 offset:27136
	v_exp_f32_e32 v227, v109
	ds_read_b128 v[180:183], v216 offset:2560
	v_add_f32_e32 v106, v231, v225
	v_mfma_f32_32x32x16_bf16 v[34:49], v[168:171], v[218:221], v[34:49]
	v_add_f32_e32 v106, v233, v106
	v_add_f32_e32 v106, v226, v106
	v_add_f32_e32 v225, v227, v106
	v_cvt_pk_bf16_f32 v164, v164, v165
	v_cvt_pk_bf16_f32 v165, v217, v230
	v_exp_f32_e32 v217, v110
	s_waitcnt lgkmcnt(0)
	v_mfma_f32_32x32x16_bf16 v[114:129], v[180:183], v[152:155], v[114:129]
	v_exp_f32_e32 v228, v111
	v_exp_f32_e32 v180, v112
	ds_read_b64_tr_b16 v[106:107], v215 offset:30720
	ds_read_b64_tr_b16 v[108:109], v215 offset:31232
	v_exp_f32_e32 v181, v113
	ds_read_b128 v[218:221], v216 offset:4096
	v_add_f32_e32 v110, v217, v225
	v_mfma_f32_32x32x16_bf16 v[2:17], v[168:171], v[98:101], v[2:17]
	v_add_f32_e32 v110, v228, v110
	v_add_f32_e32 v110, v180, v110
	v_add_f32_e32 v182, v181, v110
	v_cvt_pk_bf16_f32 v166, v232, v222
	v_cvt_pk_bf16_f32 v167, v223, v224
	s_waitcnt lgkmcnt(0)
	v_mfma_f32_32x32x16_bf16 v[130:145], v[218:221], v[156:159], v[130:145]
	v_exp_f32_e32 v183, v66
	ds_read_b64_tr_b16 v[98:99], v215 offset:59392
	ds_read_b64_tr_b16 v[100:101], v215 offset:59904
	v_exp_f32_e32 v222, v67
	ds_read_b128 v[110:113], v216 offset:4608
	v_add_f32_e32 v66, v183, v182
	v_cvt_pk_bf16_f32 v168, v231, v233
	v_mfma_f32_32x32x16_bf16 v[18:33], v[172:175], v[102:105], v[18:33]
	v_add_f32_e32 v66, v222, v66
	v_cvt_pk_bf16_f32 v169, v226, v227
	v_mfma_f32_32x32x16_bf16 v[50:65], v[172:175], v[106:109], v[50:65]
	v_exp_f32_e32 v182, v68
	ds_read_b64_tr_b16 v[102:103], v215 offset:63488
	ds_read_b64_tr_b16 v[104:105], v215 offset:64000
	v_exp_f32_e32 v218, v69
	v_cvt_pk_bf16_f32 v170, v217, v228
	v_add_f32_e32 v66, v182, v66
	v_cvt_pk_bf16_f32 v171, v180, v181
	v_add_f32_e32 v219, v218, v66
	s_waitcnt lgkmcnt(2)
	v_mfma_f32_32x32x16_bf16 v[114:129], v[110:113], v[156:159], v[114:129]
	v_exp_f32_e32 v110, v70
	ds_read_b64_tr_b16 v[66:67], v215 offset:27648
	ds_read_b64_tr_b16 v[68:69], v215 offset:28160
	v_exp_f32_e32 v111, v71
	ds_read_b128 v[106:109], v216 offset:6144
	v_add_f32_e32 v70, v110, v219
	v_add_f32_e32 v70, v111, v70
	v_mfma_f32_32x32x16_bf16 v[34:49], v[172:175], v[98:101], v[34:49]
	s_waitcnt lgkmcnt(3)
	v_mfma_f32_32x32x16_bf16 v[2:17], v[172:175], v[102:105], v[2:17]
	v_exp_f32_e32 v112, v72
	ds_read_b64_tr_b16 v[98:99], v215 offset:31744
	ds_read_b64_tr_b16 v[100:101], v215 offset:32256
	v_exp_f32_e32 v113, v73
	v_add_f32_e32 v70, v112, v70
	v_add_f32_e32 v172, v113, v70
	s_waitcnt lgkmcnt(2)
	v_mfma_f32_32x32x16_bf16 v[130:145], v[106:109], v[160:163], v[130:145]
	v_exp_f32_e32 v74, v74
	ds_read_b64_tr_b16 v[70:71], v215 offset:60416
	ds_read_b64_tr_b16 v[72:73], v215 offset:60928
	v_exp_f32_e32 v75, v75
	ds_read_b128 v[102:105], v216 offset:6656
	v_add_f32_e32 v106, v74, v172
	v_cvt_pk_bf16_f32 v172, v183, v222
	v_mfma_f32_32x32x16_bf16 v[18:33], v[176:179], v[66:69], v[18:33]
	v_add_f32_e32 v106, v75, v106
	v_cvt_pk_bf16_f32 v173, v182, v218
	s_waitcnt lgkmcnt(3)
	v_mfma_f32_32x32x16_bf16 v[50:65], v[176:179], v[98:101], v[50:65]
	v_exp_f32_e32 v76, v76
	v_exp_f32_e32 v77, v77
	ds_read_b64_tr_b16 v[66:67], v215 offset:64512
	ds_read_b64_tr_b16 v[68:69], v215 offset:65024
	v_cvt_pk_bf16_f32 v174, v110, v111
	v_add_f32_e32 v106, v76, v106
	v_add_f32_e32 v106, v77, v106
	v_cvt_pk_bf16_f32 v175, v112, v113
	s_waitcnt lgkmcnt(2)
	v_mfma_f32_32x32x16_bf16 v[114:129], v[102:105], v[160:163], v[114:129]
	v_exp_f32_e32 v78, v78
	v_exp_f32_e32 v79, v79
	v_add_f32_e32 v98, v78, v106
	v_add_f32_e32 v98, v79, v98
	v_mfma_f32_32x32x16_bf16 v[34:49], v[176:179], v[70:73], v[34:49]
	s_waitcnt lgkmcnt(0)
	v_mfma_f32_32x32x16_bf16 v[2:17], v[176:179], v[66:69], v[2:17]
	v_exp_f32_e32 v80, v80
	v_exp_f32_e32 v81, v81
	v_add_f32_e32 v66, v80, v98
	v_add_f32_e32 v66, v81, v66
	s_andn2_b64 vcc, exec, s[4:5]
	s_cbranch_vccnz .LBB0_863
	s_waitcnt lgkmcnt(0)
	ds_read_b128 v[68:71], v214 offset:96
	ds_read_b128 v[98:101], v214 offset:64
	ds_read_b128 v[102:105], v214 offset:32
	ds_read_b128 v[106:109], v214
	s_waitcnt lgkmcnt(0)
	s_waitcnt lgkmcnt(3)
	v_pk_mul_f32 v[30:31], v[30:31], v[68:69]
	s_waitcnt lgkmcnt(2)
	v_pk_mul_f32 v[26:27], v[26:27], v[98:99]
	s_waitcnt lgkmcnt(1)
	v_pk_mul_f32 v[22:23], v[22:23], v[102:103]
	v_pk_mul_f32 v[32:33], v[32:33], v[70:71]
	v_pk_mul_f32 v[28:29], v[28:29], v[100:101]
	v_pk_mul_f32 v[24:25], v[24:25], v[104:105]
	s_waitcnt lgkmcnt(0)
	v_pk_mul_f32 v[20:21], v[20:21], v[108:109]
	v_pk_mul_f32 v[18:19], v[18:19], v[106:107]
	v_pk_mul_f32 v[62:63], v[62:63], v[68:69]
	v_pk_mul_f32 v[58:59], v[58:59], v[98:99]
	v_pk_mul_f32 v[54:55], v[54:55], v[102:103]
	v_pk_mul_f32 v[64:65], v[64:65], v[70:71]
	v_pk_mul_f32 v[60:61], v[60:61], v[100:101]
	v_pk_mul_f32 v[56:57], v[56:57], v[104:105]
	v_pk_mul_f32 v[52:53], v[52:53], v[108:109]
	v_pk_mul_f32 v[50:51], v[50:51], v[106:107]
	v_pk_mul_f32 v[46:47], v[46:47], v[68:69]
	v_pk_mul_f32 v[42:43], v[42:43], v[98:99]
	v_pk_mul_f32 v[38:39], v[38:39], v[102:103]
	v_pk_mul_f32 v[48:49], v[48:49], v[70:71]
	v_pk_mul_f32 v[44:45], v[44:45], v[100:101]
	v_pk_mul_f32 v[40:41], v[40:41], v[104:105]
	v_pk_mul_f32 v[36:37], v[36:37], v[108:109]
	v_pk_mul_f32 v[34:35], v[34:35], v[106:107]
	v_pk_mul_f32 v[14:15], v[14:15], v[68:69]
	v_pk_mul_f32 v[10:11], v[10:11], v[98:99]
	v_pk_mul_f32 v[6:7], v[6:7], v[102:103]
	v_pk_mul_f32 v[16:17], v[16:17], v[70:71]
	v_pk_mul_f32 v[12:13], v[12:13], v[100:101]
	v_pk_mul_f32 v[8:9], v[8:9], v[104:105]
	v_pk_mul_f32 v[4:5], v[4:5], v[108:109]
	v_pk_mul_f32 v[2:3], v[2:3], v[106:107]

.LBB0_870:
	s_mul_hi_u32 s4, s30, 0xaaaaaaab
	s_lshr_b32 s4, s4, 1
	s_mulk_i32 s4, 0xa000
	s_add_i32 s5, s14, 0xffffa000
	s_add_i32 s4, s14, s4
	s_and_b32 s5, s5, 0x6000
	v_add_u32_e32 v194, s4, v187
	v_add_f32_e32 v192, v213, v66
	v_add_u32_e32 v193, s5, v209
	v_add_u32_e32 v194, 0xffffe000, v194
	ds_read_b64_tr_b16 v[70:71], v193 offset:24576
	ds_read_b64_tr_b16 v[72:73], v193 offset:25088
	ds_read_b64_tr_b16 v[98:99], v193 offset:28672
	ds_read_b64_tr_b16 v[100:101], v193 offset:29184
	ds_read_b128 v[66:69], v194
	s_waitcnt lgkmcnt(3)
	v_mfma_f32_32x32x16_bf16 v[18:33], v[164:167], v[70:73], v[18:33]
	ds_read_b64_tr_b16 v[102:103], v193 offset:57344
	ds_read_b64_tr_b16 v[104:105], v193 offset:57856
	s_waitcnt lgkmcnt(3)
	v_mfma_f32_32x32x16_bf16 v[50:65], v[164:167], v[98:101], v[50:65]
	ds_read_b64_tr_b16 v[106:107], v193 offset:61440
	ds_read_b64_tr_b16 v[108:109], v193 offset:61952
	s_waitcnt lgkmcnt(2)
	v_mfma_f32_32x32x16_bf16 v[34:49], v[164:167], v[102:105], v[34:49]
	ds_read_b64_tr_b16 v[70:71], v193 offset:25600
	ds_read_b64_tr_b16 v[72:73], v193 offset:26112
	s_waitcnt lgkmcnt(2)
	v_mfma_f32_32x32x16_bf16 v[2:17], v[164:167], v[106:109], v[2:17]
	ds_read_b64_tr_b16 v[180:181], v193 offset:29696
	ds_read_b64_tr_b16 v[182:183], v193 offset:30208
	v_max_f32_e32 v98, v130, v131
	v_max3_f32 v99, v132, v133, v115
	v_max3_f32 v98, v98, v114, v116
	v_max3_f32 v98, v98, v117, v134
	v_max3_f32 v99, v99, v136, v137
	v_max3_f32 v98, v98, v135, v118
	v_max3_f32 v99, v99, v120, v121
	v_max3_f32 v98, v98, v119, v138
	v_max3_f32 v99, v99, v140, v141
	v_max3_f32 v98, v98, v139, v122
	v_max3_f32 v99, v99, v124, v125
	v_max3_f32 v98, v98, v123, v142
	v_max3_f32 v99, v99, v144, v145
	v_max3_f32 v98, v98, v143, v126
	v_max3_f32 v99, v99, v128, v129
	v_max3_f32 v98, v98, v127, v99
	v_mov_b32_e32 v99, v98
	s_nop 1
	v_permlane32_swap_b32_e32 v98, v99
	v_max_f32_e32 v98, v98, v99
	v_cmp_lt_f32_e32 vcc, s15, v98
	s_cmp_lg_u64 vcc, 0
	s_cselect_b64 s[4:5], -1, 0
	s_cbranch_vccz .LBB0_874
	v_max_f32_e32 v82, v98, v98
	v_max_f32_e32 v98, 0, v82
	v_exp_f32_e64 v99, -v98
	v_add_f32_e32 v210, v210, v98
	v_xor_b32_e32 v82, 0x80000000, v210
	v_mov_b32_e32 v83, v82
	v_mov_b32_e32 v84, v82
	v_mov_b32_e32 v85, v82
	v_mov_b32_e32 v86, v82
	v_mov_b32_e32 v87, v82
	v_mov_b32_e32 v88, v82
	v_mov_b32_e32 v89, v82
	v_mov_b32_e32 v90, v82
	v_mov_b32_e32 v91, v82
	v_mov_b32_e32 v92, v82
	v_mov_b32_e32 v93, v82
	v_mov_b32_e32 v94, v82
	v_mov_b32_e32 v95, v82
	v_mov_b32_e32 v96, v82
	v_mov_b32_e32 v97, v82
	s_and_saveexec_b64 s[22:23], s[6:7]
	ds_write_b32 v147, v99
	s_or_b64 exec, exec, s[22:23]
	v_sub_f32_e32 v145, v145, v98
	v_sub_f32_e32 v144, v144, v98
	v_sub_f32_e32 v143, v143, v98
	v_sub_f32_e32 v142, v142, v98
	v_sub_f32_e32 v141, v141, v98
	v_sub_f32_e32 v140, v140, v98
	v_sub_f32_e32 v139, v139, v98
	v_sub_f32_e32 v138, v138, v98
	v_sub_f32_e32 v137, v137, v98
	v_sub_f32_e32 v136, v136, v98
	v_sub_f32_e32 v135, v135, v98
	v_sub_f32_e32 v134, v134, v98
	v_sub_f32_e32 v133, v133, v98
	v_sub_f32_e32 v132, v132, v98
	v_sub_f32_e32 v131, v131, v98
	v_sub_f32_e32 v130, v130, v98
	v_sub_f32_e32 v129, v129, v98
	v_sub_f32_e32 v128, v128, v98
	v_sub_f32_e32 v127, v127, v98
	v_sub_f32_e32 v126, v126, v98
	v_sub_f32_e32 v125, v125, v98
	v_sub_f32_e32 v124, v124, v98
	v_sub_f32_e32 v123, v123, v98
	v_sub_f32_e32 v122, v122, v98
	v_sub_f32_e32 v121, v121, v98
	v_sub_f32_e32 v120, v120, v98
	v_sub_f32_e32 v119, v119, v98
	v_sub_f32_e32 v118, v118, v98
	v_sub_f32_e32 v117, v117, v98
	v_sub_f32_e32 v116, v116, v98
	v_sub_f32_e32 v115, v115, v98
	v_sub_f32_e32 v114, v114, v98
	v_mul_f32_e32 v192, v192, v99
.LBB0_874:
	v_cvt_pk_bf16_f32 v176, v74, v75
	v_cvt_pk_bf16_f32 v177, v76, v77
	v_cvt_pk_bf16_f32 v178, v78, v79
	v_cvt_pk_bf16_f32 v179, v80, v81
	v_exp_f32_e32 v164, v130
	v_mfma_f32_32x32x16_bf16 v[98:113], v[66:69], v[148:151], v[82:97]
	v_exp_f32_e32 v165, v131
	v_exp_f32_e32 v195, v132
	ds_read_b64_tr_b16 v[216:217], v193 offset:58368
	ds_read_b64_tr_b16 v[218:219], v193 offset:58880
	v_exp_f32_e32 v213, v133
	ds_read_b128 v[220:223], v194 offset:512
	s_waitcnt lgkmcnt(5)
	v_mfma_f32_32x32x16_bf16 v[18:33], v[168:171], v[70:73], v[18:33]
	v_add_f32_e32 v66, v165, v164
	v_add_f32_e32 v66, v195, v66
	v_add_f32_e32 v215, v213, v66
	ds_read_b64_tr_b16 v[130:131], v193 offset:62464
	ds_read_b64_tr_b16 v[132:133], v193 offset:62976
	ds_read_b128 v[224:227], v194 offset:2048
	v_exp_f32_e32 v228, v134
	s_waitcnt lgkmcnt(3)
	v_mfma_f32_32x32x16_bf16 v[66:81], v[220:223], v[148:151], v[82:97]
	v_exp_f32_e32 v220, v135
	v_exp_f32_e32 v221, v136
	v_exp_f32_e32 v222, v137
	v_add_f32_e32 v134, v228, v215
	v_add_f32_e32 v134, v220, v134
	v_add_f32_e32 v134, v221, v134
	v_add_f32_e32 v215, v222, v134
	v_mfma_f32_32x32x16_bf16 v[50:65], v[168:171], v[180:183], v[50:65]
	v_exp_f32_e32 v223, v138
	s_waitcnt lgkmcnt(0)
	v_mfma_f32_32x32x16_bf16 v[98:113], v[224:227], v[152:155], v[98:113]
	v_exp_f32_e32 v229, v139
	v_exp_f32_e32 v224, v140
	ds_read_b64_tr_b16 v[134:135], v193 offset:26624
	ds_read_b64_tr_b16 v[136:137], v193 offset:27136
	v_exp_f32_e32 v225, v141
	ds_read_b128 v[180:183], v194 offset:2560
	v_add_f32_e32 v138, v223, v215
	v_mfma_f32_32x32x16_bf16 v[34:49], v[168:171], v[216:219], v[34:49]
	v_add_f32_e32 v138, v229, v138
	v_add_f32_e32 v138, v224, v138
	v_add_f32_e32 v215, v225, v138
	v_cvt_pk_bf16_f32 v164, v164, v165
	v_cvt_pk_bf16_f32 v165, v195, v213
	v_exp_f32_e32 v195, v142
	s_waitcnt lgkmcnt(0)
	v_mfma_f32_32x32x16_bf16 v[66:81], v[180:183], v[152:155], v[66:81]
	v_exp_f32_e32 v213, v143
	v_exp_f32_e32 v180, v144
	ds_read_b64_tr_b16 v[138:139], v193 offset:30720
	ds_read_b64_tr_b16 v[140:141], v193 offset:31232
	v_exp_f32_e32 v181, v145
	ds_read_b128 v[216:219], v194 offset:4096
	v_add_f32_e32 v142, v195, v215
	v_mfma_f32_32x32x16_bf16 v[2:17], v[168:171], v[130:133], v[2:17]
	v_add_f32_e32 v142, v213, v142
	v_add_f32_e32 v142, v180, v142
	v_add_f32_e32 v182, v181, v142
	v_cvt_pk_bf16_f32 v166, v228, v220
	v_cvt_pk_bf16_f32 v167, v221, v222
	s_waitcnt lgkmcnt(0)
	v_mfma_f32_32x32x16_bf16 v[98:113], v[216:219], v[156:159], v[98:113]
	v_exp_f32_e32 v183, v114
	ds_read_b64_tr_b16 v[130:131], v193 offset:59392
	ds_read_b64_tr_b16 v[132:133], v193 offset:59904
	v_exp_f32_e32 v215, v115
	ds_read_b128 v[142:145], v194 offset:4608
	v_add_f32_e32 v114, v183, v182
	v_cvt_pk_bf16_f32 v168, v223, v229
	v_mfma_f32_32x32x16_bf16 v[18:33], v[172:175], v[134:137], v[18:33]
	v_add_f32_e32 v114, v215, v114
	v_cvt_pk_bf16_f32 v169, v224, v225
	v_mfma_f32_32x32x16_bf16 v[50:65], v[172:175], v[138:141], v[50:65]
	v_exp_f32_e32 v182, v116
	ds_read_b64_tr_b16 v[134:135], v193 offset:63488
	ds_read_b64_tr_b16 v[136:137], v193 offset:64000
	v_exp_f32_e32 v216, v117
	v_cvt_pk_bf16_f32 v170, v195, v213
	v_add_f32_e32 v114, v182, v114
	v_cvt_pk_bf16_f32 v171, v180, v181
	v_add_f32_e32 v114, v216, v114
	s_waitcnt lgkmcnt(2)
	v_mfma_f32_32x32x16_bf16 v[66:81], v[142:145], v[156:159], v[66:81]
	v_exp_f32_e32 v142, v118
	ds_read_b64_tr_b16 v[138:139], v193 offset:27648
	ds_read_b64_tr_b16 v[140:141], v193 offset:28160
	v_exp_f32_e32 v143, v119
	ds_read_b128 v[116:119], v194 offset:6144
	v_add_f32_e32 v114, v142, v114
	v_add_f32_e32 v114, v143, v114
	v_mfma_f32_32x32x16_bf16 v[34:49], v[172:175], v[130:133], v[34:49]
	s_waitcnt lgkmcnt(3)
	v_mfma_f32_32x32x16_bf16 v[2:17], v[172:175], v[134:137], v[2:17]
	v_exp_f32_e32 v144, v120
	ds_read_b64_tr_b16 v[130:131], v193 offset:31744
	ds_read_b64_tr_b16 v[132:133], v193 offset:32256
	v_exp_f32_e32 v145, v121
	v_add_f32_e32 v114, v144, v114
	v_add_f32_e32 v172, v145, v114
	s_waitcnt lgkmcnt(2)
	v_mfma_f32_32x32x16_bf16 v[98:113], v[116:119], v[160:163], v[98:113]
	v_exp_f32_e32 v114, v122
	ds_read_b64_tr_b16 v[134:135], v193 offset:60416
	ds_read_b64_tr_b16 v[136:137], v193 offset:60928
	v_exp_f32_e32 v115, v123
	ds_read_b128 v[118:121], v194 offset:6656
	v_add_f32_e32 v116, v114, v172
	v_cvt_pk_bf16_f32 v172, v183, v215
	v_mfma_f32_32x32x16_bf16 v[18:33], v[176:179], v[138:141], v[18:33]
	v_add_f32_e32 v180, v115, v116
	v_cvt_pk_bf16_f32 v173, v182, v216
	s_waitcnt lgkmcnt(3)
	v_mfma_f32_32x32x16_bf16 v[50:65], v[176:179], v[130:133], v[50:65]
	v_exp_f32_e32 v116, v124
	v_exp_f32_e32 v117, v125
	ds_read_b64_tr_b16 v[122:123], v193 offset:64512
	ds_read_b64_tr_b16 v[124:125], v193 offset:65024
	v_cvt_pk_bf16_f32 v174, v142, v143
	v_add_f32_e32 v138, v116, v180
	v_add_f32_e32 v138, v117, v138
	v_cvt_pk_bf16_f32 v175, v144, v145
	s_waitcnt lgkmcnt(2)
	v_mfma_f32_32x32x16_bf16 v[66:81], v[118:121], v[160:163], v[66:81]
	v_exp_f32_e32 v118, v126
	v_exp_f32_e32 v119, v127
	v_add_f32_e32 v120, v118, v138
	v_add_f32_e32 v126, v119, v120
	v_mfma_f32_32x32x16_bf16 v[34:49], v[176:179], v[134:137], v[34:49]
	s_waitcnt lgkmcnt(0)
	v_mfma_f32_32x32x16_bf16 v[2:17], v[176:179], v[122:125], v[2:17]
	v_exp_f32_e32 v120, v128
	v_exp_f32_e32 v121, v129
	v_add_f32_e32 v122, v120, v126
	v_add_f32_e32 v122, v121, v122
	s_andn2_b64 vcc, exec, s[4:5]
	s_cbranch_vccnz .LBB0_876
	s_waitcnt lgkmcnt(0)
	ds_read_b128 v[124:127], v214 offset:96
	ds_read_b128 v[128:131], v214 offset:64
	ds_read_b128 v[132:135], v214
	ds_read_b128 v[136:139], v214 offset:32
	s_waitcnt lgkmcnt(0)
	s_waitcnt lgkmcnt(3)
	v_pk_mul_f32 v[32:33], v[32:33], v[126:127]
	v_pk_mul_f32 v[30:31], v[30:31], v[124:125]
	s_waitcnt lgkmcnt(2)
	v_pk_mul_f32 v[28:29], v[28:29], v[130:131]
	v_pk_mul_f32 v[26:27], v[26:27], v[128:129]
	s_waitcnt lgkmcnt(0)
	v_pk_mul_f32 v[24:25], v[24:25], v[138:139]
	v_pk_mul_f32 v[22:23], v[22:23], v[136:137]
	v_pk_mul_f32 v[20:21], v[20:21], v[134:135]
	v_pk_mul_f32 v[18:19], v[18:19], v[132:133]
	v_pk_mul_f32 v[64:65], v[64:65], v[126:127]
	v_pk_mul_f32 v[62:63], v[62:63], v[124:125]
	v_pk_mul_f32 v[60:61], v[60:61], v[130:131]
	v_pk_mul_f32 v[58:59], v[58:59], v[128:129]
	v_pk_mul_f32 v[56:57], v[56:57], v[138:139]
	v_pk_mul_f32 v[54:55], v[54:55], v[136:137]
	v_pk_mul_f32 v[52:53], v[52:53], v[134:135]
	v_pk_mul_f32 v[50:51], v[50:51], v[132:133]
	v_pk_mul_f32 v[48:49], v[48:49], v[126:127]
	v_pk_mul_f32 v[46:47], v[46:47], v[124:125]
	v_pk_mul_f32 v[44:45], v[44:45], v[130:131]
	v_pk_mul_f32 v[42:43], v[42:43], v[128:129]
	v_pk_mul_f32 v[40:41], v[40:41], v[138:139]
	v_pk_mul_f32 v[38:39], v[38:39], v[136:137]
	v_pk_mul_f32 v[36:37], v[36:37], v[134:135]
	v_pk_mul_f32 v[34:35], v[34:35], v[132:133]
	v_pk_mul_f32 v[16:17], v[16:17], v[126:127]
	v_pk_mul_f32 v[14:15], v[14:15], v[124:125]
	v_pk_mul_f32 v[12:13], v[12:13], v[130:131]
	v_pk_mul_f32 v[10:11], v[10:11], v[128:129]
	v_pk_mul_f32 v[8:9], v[8:9], v[138:139]
	v_pk_mul_f32 v[6:7], v[6:7], v[136:137]
	v_pk_mul_f32 v[4:5], v[4:5], v[134:135]
	v_pk_mul_f32 v[2:3], v[2:3], v[132:133]

.LBB0_893:
	v_add_u32_e32 v189, s4, v209
	ds_read_b64_tr_b16 v[82:83], v189 offset:24576
	ds_read_b64_tr_b16 v[84:85], v189 offset:25088
	ds_read_b64_tr_b16 v[86:87], v189 offset:28672
	ds_read_b64_tr_b16 v[88:89], v189 offset:29184
	s_waitcnt lgkmcnt(2)
	v_mfma_f32_32x32x16_bf16 v[18:33], v[164:167], v[82:85], v[18:33]
	ds_read_b64_tr_b16 v[90:91], v189 offset:57344
	ds_read_b64_tr_b16 v[92:93], v189 offset:57856
	s_waitcnt lgkmcnt(2)
	v_mfma_f32_32x32x16_bf16 v[50:65], v[164:167], v[86:89], v[50:65]
	ds_read_b64_tr_b16 v[82:83], v189 offset:61440
	ds_read_b64_tr_b16 v[84:85], v189 offset:61952
	s_waitcnt lgkmcnt(2)
	v_mfma_f32_32x32x16_bf16 v[34:49], v[164:167], v[90:93], v[34:49]
	ds_read_b64_tr_b16 v[184:185], v189 offset:25600
	ds_read_b64_tr_b16 v[186:187], v189 offset:26112
	s_waitcnt lgkmcnt(2)
	v_mfma_f32_32x32x16_bf16 v[2:17], v[164:167], v[82:85], v[2:17]
	ds_read_b64_tr_b16 v[180:181], v189 offset:29696
	ds_read_b64_tr_b16 v[182:183], v189 offset:30208
	v_max_f32_e32 v82, v98, v99
	v_max3_f32 v83, v100, v101, v67
	v_max3_f32 v82, v82, v66, v68
	v_max3_f32 v82, v82, v69, v102
	v_max3_f32 v83, v83, v104, v105
	v_max3_f32 v82, v82, v103, v70
	v_max3_f32 v83, v83, v72, v73
	v_max3_f32 v82, v82, v71, v106
	v_max3_f32 v83, v83, v108, v109
	v_max3_f32 v82, v82, v107, v74
	v_max3_f32 v83, v83, v76, v77
	v_max3_f32 v82, v82, v75, v110
	v_max3_f32 v83, v83, v112, v113
	v_max3_f32 v82, v82, v111, v78
	v_max3_f32 v83, v83, v80, v81
	v_max3_f32 v82, v82, v79, v83
	v_mov_b32_e32 v83, v82
	s_nop 1
	v_permlane32_swap_b32_e32 v82, v83
	v_max_f32_e32 v82, v82, v83
	v_cmp_lt_f32_e32 vcc, s15, v82
	s_cmp_lg_u64 vcc, 0
	s_cselect_b64 s[4:5], -1, 0
	s_cbranch_vccz .LBB0_897
	v_max_f32_e32 v82, v82, v82
	v_max_f32_e32 v164, 0, v82
	v_exp_f32_e64 v165, -v164
	v_add_f32_e32 v82, v210, v164
	v_xor_b32_e32 v82, 0x80000000, v82
	v_mov_b32_e32 v83, v82
	v_mov_b32_e32 v84, v82
	v_mov_b32_e32 v85, v82
	v_mov_b32_e32 v86, v82
	v_mov_b32_e32 v87, v82
	v_mov_b32_e32 v88, v82
	v_mov_b32_e32 v89, v82
	v_mov_b32_e32 v90, v82
	v_mov_b32_e32 v91, v82
	v_mov_b32_e32 v92, v82
	v_mov_b32_e32 v93, v82
	v_mov_b32_e32 v94, v82
	v_mov_b32_e32 v95, v82
	v_mov_b32_e32 v96, v82
	v_mov_b32_e32 v97, v82
	v_cmp_gt_u32_e32 vcc, 32, v1
	s_and_saveexec_b64 s[6:7], vcc
	ds_write_b32 v147, v165
	s_or_b64 exec, exec, s[6:7]
	v_sub_f32_e32 v113, v113, v164
	v_sub_f32_e32 v112, v112, v164
	v_sub_f32_e32 v111, v111, v164
	v_sub_f32_e32 v110, v110, v164
	v_sub_f32_e32 v109, v109, v164
	v_sub_f32_e32 v108, v108, v164
	v_sub_f32_e32 v107, v107, v164
	v_sub_f32_e32 v106, v106, v164
	v_sub_f32_e32 v105, v105, v164
	v_sub_f32_e32 v104, v104, v164
	v_sub_f32_e32 v103, v103, v164
	v_sub_f32_e32 v102, v102, v164
	v_sub_f32_e32 v101, v101, v164
	v_sub_f32_e32 v100, v100, v164
	v_sub_f32_e32 v99, v99, v164
	v_sub_f32_e32 v98, v98, v164
	v_sub_f32_e32 v81, v81, v164
	v_sub_f32_e32 v80, v80, v164
	v_sub_f32_e32 v79, v79, v164
	v_sub_f32_e32 v78, v78, v164
	v_sub_f32_e32 v77, v77, v164
	v_sub_f32_e32 v76, v76, v164
	v_sub_f32_e32 v75, v75, v164
	v_sub_f32_e32 v74, v74, v164
	v_sub_f32_e32 v73, v73, v164
	v_sub_f32_e32 v72, v72, v164
	v_sub_f32_e32 v71, v71, v164
	v_sub_f32_e32 v70, v70, v164
	v_sub_f32_e32 v69, v69, v164
	v_sub_f32_e32 v68, v68, v164
	v_sub_f32_e32 v67, v67, v164
	v_sub_f32_e32 v66, v66, v164
	v_mul_f32_e32 v213, v213, v165
.LBB0_897:
	v_exp_f32_e32 v94, v98
	s_waitcnt lgkmcnt(2)
	v_mfma_f32_32x32x16_bf16 v[18:33], v[168:171], v[184:187], v[18:33]
	v_exp_f32_e32 v95, v99
	v_exp_f32_e32 v96, v100
	ds_read_b64_tr_b16 v[82:83], v189 offset:58368
	ds_read_b64_tr_b16 v[84:85], v189 offset:58880
	v_exp_f32_e32 v97, v101
	v_add_f32_e32 v86, v95, v94
	v_add_f32_e32 v86, v96, v86
	v_add_f32_e32 v90, v97, v86
	v_exp_f32_e32 v98, v102
	s_waitcnt lgkmcnt(2)
	v_mfma_f32_32x32x16_bf16 v[50:65], v[168:171], v[180:183], v[50:65]
	v_exp_f32_e32 v99, v103
	v_exp_f32_e32 v100, v104
	ds_read_b64_tr_b16 v[86:87], v189 offset:62464
	ds_read_b64_tr_b16 v[88:89], v189 offset:62976
	v_exp_f32_e32 v101, v105
	v_add_f32_e32 v90, v98, v90
	v_add_f32_e32 v90, v99, v90
	v_add_f32_e32 v90, v100, v90
	v_add_f32_e32 v102, v101, v90
	v_exp_f32_e32 v103, v106
	s_waitcnt lgkmcnt(2)
	v_mfma_f32_32x32x16_bf16 v[34:49], v[168:171], v[82:85], v[34:49]
	v_exp_f32_e32 v104, v107
	v_exp_f32_e32 v105, v108
	ds_read_b64_tr_b16 v[90:91], v189 offset:26624
	ds_read_b64_tr_b16 v[92:93], v189 offset:27136
	v_exp_f32_e32 v106, v109
	v_add_f32_e32 v82, v103, v102
	v_add_f32_e32 v82, v104, v82
	v_add_f32_e32 v82, v105, v82
	v_add_f32_e32 v102, v106, v82
	v_cvt_pk_bf16_f32 v164, v94, v95
	v_cvt_pk_bf16_f32 v165, v96, v97
	v_exp_f32_e32 v94, v110
	s_waitcnt lgkmcnt(2)
	v_mfma_f32_32x32x16_bf16 v[2:17], v[168:171], v[86:89], v[2:17]
	v_exp_f32_e32 v95, v111
	v_exp_f32_e32 v96, v112
	ds_read_b64_tr_b16 v[82:83], v189 offset:30720
	ds_read_b64_tr_b16 v[84:85], v189 offset:31232
	v_exp_f32_e32 v97, v113
	v_add_f32_e32 v86, v94, v102
	v_add_f32_e32 v86, v95, v86
	v_add_f32_e32 v86, v96, v86
	v_add_f32_e32 v102, v97, v86
	v_cvt_pk_bf16_f32 v166, v98, v99
	v_cvt_pk_bf16_f32 v167, v100, v101
	s_waitcnt lgkmcnt(2)
	v_mfma_f32_32x32x16_bf16 v[18:33], v[172:175], v[90:93], v[18:33]
	v_exp_f32_e32 v98, v66
	v_exp_f32_e32 v99, v67
	ds_read_b64_tr_b16 v[86:87], v189 offset:59392
	ds_read_b64_tr_b16 v[88:89], v189 offset:59904
	v_cvt_pk_bf16_f32 v168, v103, v104
	v_add_f32_e32 v66, v98, v102
	v_add_f32_e32 v100, v99, v66
	v_cvt_pk_bf16_f32 v169, v105, v106
	s_waitcnt lgkmcnt(2)
	v_mfma_f32_32x32x16_bf16 v[50:65], v[172:175], v[82:85], v[50:65]
	v_exp_f32_e32 v101, v68
	v_exp_f32_e32 v102, v69
	ds_read_b64_tr_b16 v[66:67], v189 offset:63488
	ds_read_b64_tr_b16 v[68:69], v189 offset:64000
	v_cvt_pk_bf16_f32 v170, v94, v95
	v_add_f32_e32 v90, v101, v100
	v_add_f32_e32 v90, v102, v90
	v_cvt_pk_bf16_f32 v171, v96, v97
	s_waitcnt lgkmcnt(2)
	v_mfma_f32_32x32x16_bf16 v[34:49], v[172:175], v[86:89], v[34:49]
	v_exp_f32_e32 v94, v70
	v_exp_f32_e32 v95, v71
	ds_read_b64_tr_b16 v[82:83], v189 offset:27648
	ds_read_b64_tr_b16 v[84:85], v189 offset:28160
	v_add_f32_e32 v70, v94, v90
	v_add_f32_e32 v70, v95, v70
	s_waitcnt lgkmcnt(2)
	v_mfma_f32_32x32x16_bf16 v[2:17], v[172:175], v[66:69], v[2:17]
	v_exp_f32_e32 v72, v72
	v_exp_f32_e32 v73, v73
	ds_read_b64_tr_b16 v[86:87], v189 offset:31744
	ds_read_b64_tr_b16 v[88:89], v189 offset:32256
	v_add_f32_e32 v70, v72, v70
	v_add_f32_e32 v70, v73, v70
	s_waitcnt lgkmcnt(2)
	v_mfma_f32_32x32x16_bf16 v[18:33], v[176:179], v[82:85], v[18:33]
	v_exp_f32_e32 v68, v74
	v_exp_f32_e32 v69, v75
	ds_read_b64_tr_b16 v[90:91], v189 offset:60416
	ds_read_b64_tr_b16 v[92:93], v189 offset:60928
	v_cvt_pk_bf16_f32 v172, v98, v99
	v_add_f32_e32 v66, v68, v70
	v_add_f32_e32 v66, v69, v66
	v_cvt_pk_bf16_f32 v173, v101, v102
	s_waitcnt lgkmcnt(2)
	v_mfma_f32_32x32x16_bf16 v[50:65], v[176:179], v[86:89], v[50:65]
	v_exp_f32_e32 v70, v76
	v_exp_f32_e32 v71, v77
	ds_read_b64_tr_b16 v[82:83], v189 offset:64512
	ds_read_b64_tr_b16 v[84:85], v189 offset:65024
	v_cvt_pk_bf16_f32 v174, v94, v95
	v_add_f32_e32 v66, v70, v66
	v_add_f32_e32 v66, v71, v66
	v_cvt_pk_bf16_f32 v175, v72, v73
	s_waitcnt lgkmcnt(2)
	v_mfma_f32_32x32x16_bf16 v[34:49], v[176:179], v[90:93], v[34:49]
	v_exp_f32_e32 v72, v78
	v_exp_f32_e32 v73, v79
	v_add_f32_e32 v66, v72, v66
	v_add_f32_e32 v66, v73, v66
	s_waitcnt lgkmcnt(0)
	v_mfma_f32_32x32x16_bf16 v[2:17], v[176:179], v[82:85], v[2:17]
	v_exp_f32_e32 v74, v80
	v_exp_f32_e32 v75, v81
	v_add_f32_e32 v66, v74, v66
	v_add_f32_e32 v67, v75, v66
	s_andn2_b64 vcc, exec, s[4:5]
	v_lshl_add_u32 v66, v208, 4, s20
	s_cbranch_vccnz .LBB0_899
	s_waitcnt lgkmcnt(0)
	ds_read_b128 v[76:79], v66 offset:96
	ds_read_b128 v[80:83], v66 offset:64
	ds_read_b128 v[84:87], v66 offset:32
	ds_read_b128 v[88:91], v66
	s_waitcnt lgkmcnt(0)
	s_waitcnt lgkmcnt(3)
	v_pk_mul_f32 v[32:33], v[32:33], v[78:79]
	s_waitcnt lgkmcnt(2)
	v_pk_mul_f32 v[28:29], v[28:29], v[82:83]
	s_waitcnt lgkmcnt(1)
	v_pk_mul_f32 v[24:25], v[24:25], v[86:87]
	s_waitcnt lgkmcnt(0)
	v_pk_mul_f32 v[20:21], v[20:21], v[90:91]
	v_pk_mul_f32 v[30:31], v[30:31], v[76:77]
	v_pk_mul_f32 v[26:27], v[26:27], v[80:81]
	v_pk_mul_f32 v[22:23], v[22:23], v[84:85]
	v_pk_mul_f32 v[18:19], v[18:19], v[88:89]
	v_pk_mul_f32 v[64:65], v[64:65], v[78:79]
	v_pk_mul_f32 v[60:61], v[60:61], v[82:83]
	v_pk_mul_f32 v[56:57], v[56:57], v[86:87]
	v_pk_mul_f32 v[52:53], v[52:53], v[90:91]
	v_pk_mul_f32 v[62:63], v[62:63], v[76:77]
	v_pk_mul_f32 v[58:59], v[58:59], v[80:81]
	v_pk_mul_f32 v[54:55], v[54:55], v[84:85]
	v_pk_mul_f32 v[50:51], v[50:51], v[88:89]
	v_pk_mul_f32 v[48:49], v[48:49], v[78:79]
	v_pk_mul_f32 v[44:45], v[44:45], v[82:83]
	v_pk_mul_f32 v[40:41], v[40:41], v[86:87]
	v_pk_mul_f32 v[36:37], v[36:37], v[90:91]
	v_pk_mul_f32 v[46:47], v[46:47], v[76:77]
	v_pk_mul_f32 v[42:43], v[42:43], v[80:81]
	v_pk_mul_f32 v[38:39], v[38:39], v[84:85]
	v_pk_mul_f32 v[34:35], v[34:35], v[88:89]
	v_pk_mul_f32 v[16:17], v[16:17], v[78:79]
	v_pk_mul_f32 v[12:13], v[12:13], v[82:83]
	v_pk_mul_f32 v[8:9], v[8:9], v[86:87]
	v_pk_mul_f32 v[4:5], v[4:5], v[90:91]
	v_pk_mul_f32 v[14:15], v[14:15], v[76:77]
	v_pk_mul_f32 v[10:11], v[10:11], v[80:81]
	v_pk_mul_f32 v[6:7], v[6:7], v[84:85]
	v_pk_mul_f32 v[2:3], v[2:3], v[88:89]
